# conformer conv31 prompt chain: packed f32 FMAs (two outputs per instruction, tap weight broadcast by op_sel), 61 pair reads from LDS running 6 ahead
# speedup vs baseline: 1.0090x; 1.0040x over previous
; #define LAS __attribute__((address_space(3)))
;     static __device__ __forceinline__ void run(float (&acc)[32], const float (&w)[31], const LAS float* us) {
;         const float v = us[J * 512];
;         constexpr int TLO = (J - 30 > 0) ? J - 30 : 0, THI = (J < 31) ? J : 31;
; #pragma unroll
;         for (int t = TLO; t <= THI; ++t) acc[t] += v * w[J - t];
;         if constexpr (J + 1 < 62) CfLds<J + 1>::run(acc, w, us);
;     }
; __device__ __forceinline__ void cf_prompt_items(LAS unsigned char* lds, const bf16_t* PROJ, int it0, int itstride, int nitems, const float* cw, const float* cb, bf16_t* CONVOUT, float* pcfc) {
;     ...
;         float acc[32];
; #pragma unroll
;         for (int t = 0; t < 32; ++t) acc[t] = bias;
;         CfLds<0>::run(acc, wv, Us + tid);
.LBB0_242:
	v_add_u32_e32 v160, 0x8000, v52
	ds_read2st64_b32 v[144:145], v52 offset0:0 offset1:8
	ds_read2st64_b32 v[146:147], v52 offset0:8 offset1:16
	ds_read2st64_b32 v[148:149], v52 offset0:16 offset1:24
	ds_read2st64_b32 v[150:151], v52 offset0:24 offset1:32
	ds_read2st64_b32 v[152:153], v52 offset0:32 offset1:40
	ds_read2st64_b32 v[154:155], v52 offset0:40 offset1:48
	s_and_b32 s82, s75, 0xffffffe0
	s_lshl_b32 s38, s83, 1
	s_ashr_i32 s83, s82, 31
	s_lshl_b64 s[0:1], s[82:83], 12
	s_waitcnt vmcnt(0)
	s_andn2_b64 vcc, exec, s[80:81]
	s_mov_b32 s33, s93
	ds_read2st64_b32 v[156:157], v52 offset0:48 offset1:56
	s_waitcnt lgkmcnt(6)
	v_pk_fma_f32 v[176:177], v[144:145], v[142:143], v[90:91] op_sel:[0,1,1] op_sel_hi:[1,1,1]
	ds_read2st64_b32 v[158:159], v52 offset0:56 offset1:64
	s_waitcnt lgkmcnt(6)
	v_pk_fma_f32 v[176:177], v[146:147], v[142:143], v[176:177] op_sel:[0,0,0] op_sel_hi:[1,0,1]
	ds_read2st64_b32 v[144:145], v52 offset0:64 offset1:72
	s_waitcnt lgkmcnt(6)
	v_pk_fma_f32 v[176:177], v[148:149], v[140:141], v[176:177] op_sel:[0,1,0] op_sel_hi:[1,1,1]
	v_pk_fma_f32 v[178:179], v[148:149], v[142:143], v[90:91] op_sel:[0,1,1] op_sel_hi:[1,1,1]
	ds_read2st64_b32 v[146:147], v52 offset0:72 offset1:80
	s_waitcnt lgkmcnt(6)
	v_pk_fma_f32 v[176:177], v[150:151], v[140:141], v[176:177] op_sel:[0,0,0] op_sel_hi:[1,0,1]
	v_pk_fma_f32 v[178:179], v[150:151], v[142:143], v[178:179] op_sel:[0,0,0] op_sel_hi:[1,0,1]
	ds_read2st64_b32 v[148:149], v52 offset0:80 offset1:88
	s_waitcnt lgkmcnt(6)
	v_pk_fma_f32 v[176:177], v[152:153], v[138:139], v[176:177] op_sel:[0,1,0] op_sel_hi:[1,1,1]
	v_pk_fma_f32 v[178:179], v[152:153], v[140:141], v[178:179] op_sel:[0,1,0] op_sel_hi:[1,1,1]
	v_pk_fma_f32 v[180:181], v[152:153], v[142:143], v[90:91] op_sel:[0,1,1] op_sel_hi:[1,1,1]
	ds_read2st64_b32 v[150:151], v52 offset0:88 offset1:96
	s_waitcnt lgkmcnt(6)
	v_pk_fma_f32 v[176:177], v[154:155], v[138:139], v[176:177] op_sel:[0,0,0] op_sel_hi:[1,0,1]
	v_pk_fma_f32 v[178:179], v[154:155], v[140:141], v[178:179] op_sel:[0,0,0] op_sel_hi:[1,0,1]
	v_pk_fma_f32 v[180:181], v[154:155], v[142:143], v[180:181] op_sel:[0,0,0] op_sel_hi:[1,0,1]
	ds_read2st64_b32 v[152:153], v52 offset0:96 offset1:104
	s_waitcnt lgkmcnt(6)
	v_pk_fma_f32 v[176:177], v[156:157], v[136:137], v[176:177] op_sel:[0,1,0] op_sel_hi:[1,1,1]
	v_pk_fma_f32 v[178:179], v[156:157], v[138:139], v[178:179] op_sel:[0,1,0] op_sel_hi:[1,1,1]
	v_pk_fma_f32 v[180:181], v[156:157], v[140:141], v[180:181] op_sel:[0,1,0] op_sel_hi:[1,1,1]
	v_pk_fma_f32 v[182:183], v[156:157], v[142:143], v[90:91] op_sel:[0,1,1] op_sel_hi:[1,1,1]
	ds_read2st64_b32 v[154:155], v52 offset0:104 offset1:112
	s_waitcnt lgkmcnt(6)
	v_pk_fma_f32 v[176:177], v[158:159], v[136:137], v[176:177] op_sel:[0,0,0] op_sel_hi:[1,0,1]
	v_pk_fma_f32 v[178:179], v[158:159], v[138:139], v[178:179] op_sel:[0,0,0] op_sel_hi:[1,0,1]
	v_pk_fma_f32 v[180:181], v[158:159], v[140:141], v[180:181] op_sel:[0,0,0] op_sel_hi:[1,0,1]
	v_pk_fma_f32 v[182:183], v[158:159], v[142:143], v[182:183] op_sel:[0,0,0] op_sel_hi:[1,0,1]
	ds_read2st64_b32 v[156:157], v52 offset0:112 offset1:120
	s_waitcnt lgkmcnt(6)
	v_pk_fma_f32 v[176:177], v[144:145], v[126:127], v[176:177] op_sel:[0,1,0] op_sel_hi:[1,1,1]
	v_pk_fma_f32 v[178:179], v[144:145], v[136:137], v[178:179] op_sel:[0,1,0] op_sel_hi:[1,1,1]
	v_pk_fma_f32 v[180:181], v[144:145], v[138:139], v[180:181] op_sel:[0,1,0] op_sel_hi:[1,1,1]
	v_pk_fma_f32 v[182:183], v[144:145], v[140:141], v[182:183] op_sel:[0,1,0] op_sel_hi:[1,1,1]
	v_pk_fma_f32 v[184:185], v[144:145], v[142:143], v[90:91] op_sel:[0,1,1] op_sel_hi:[1,1,1]
	ds_read2st64_b32 v[158:159], v52 offset0:120 offset1:128
	s_waitcnt lgkmcnt(6)
	v_pk_fma_f32 v[176:177], v[146:147], v[126:127], v[176:177] op_sel:[0,0,0] op_sel_hi:[1,0,1]
	v_pk_fma_f32 v[178:179], v[146:147], v[136:137], v[178:179] op_sel:[0,0,0] op_sel_hi:[1,0,1]
	v_pk_fma_f32 v[180:181], v[146:147], v[138:139], v[180:181] op_sel:[0,0,0] op_sel_hi:[1,0,1]
	v_pk_fma_f32 v[182:183], v[146:147], v[140:141], v[182:183] op_sel:[0,0,0] op_sel_hi:[1,0,1]
	v_pk_fma_f32 v[184:185], v[146:147], v[142:143], v[184:185] op_sel:[0,0,0] op_sel_hi:[1,0,1]
	ds_read2st64_b32 v[144:145], v52 offset0:128 offset1:136
	s_waitcnt lgkmcnt(6)
	v_pk_fma_f32 v[176:177], v[148:149], v[122:123], v[176:177] op_sel:[0,1,0] op_sel_hi:[1,1,1]
	v_pk_fma_f32 v[178:179], v[148:149], v[126:127], v[178:179] op_sel:[0,1,0] op_sel_hi:[1,1,1]
	v_pk_fma_f32 v[180:181], v[148:149], v[136:137], v[180:181] op_sel:[0,1,0] op_sel_hi:[1,1,1]
	v_pk_fma_f32 v[182:183], v[148:149], v[138:139], v[182:183] op_sel:[0,1,0] op_sel_hi:[1,1,1]
	v_pk_fma_f32 v[184:185], v[148:149], v[140:141], v[184:185] op_sel:[0,1,0] op_sel_hi:[1,1,1]
	v_pk_fma_f32 v[186:187], v[148:149], v[142:143], v[90:91] op_sel:[0,1,1] op_sel_hi:[1,1,1]
	ds_read2st64_b32 v[146:147], v52 offset0:136 offset1:144
	s_waitcnt lgkmcnt(6)
	v_pk_fma_f32 v[176:177], v[150:151], v[120:121], v[176:177] op_sel:[0,0,0] op_sel_hi:[1,0,1]
	v_pk_fma_f32 v[178:179], v[150:151], v[126:127], v[178:179] op_sel:[0,0,0] op_sel_hi:[1,0,1]
	v_pk_fma_f32 v[180:181], v[150:151], v[136:137], v[180:181] op_sel:[0,0,0] op_sel_hi:[1,0,1]
	v_pk_fma_f32 v[182:183], v[150:151], v[138:139], v[182:183] op_sel:[0,0,0] op_sel_hi:[1,0,1]
	v_pk_fma_f32 v[184:185], v[150:151], v[140:141], v[184:185] op_sel:[0,0,0] op_sel_hi:[1,0,1]
	v_pk_fma_f32 v[186:187], v[150:151], v[142:143], v[186:187] op_sel:[0,0,0] op_sel_hi:[1,0,1]
	ds_read2st64_b32 v[148:149], v52 offset0:144 offset1:152
	s_waitcnt lgkmcnt(6)
; #define LAS __attribute__((address_space(3)))
;     static __device__ __forceinline__ void run(float (&acc)[32], const float (&w)[31], const LAS float* us) {
;         const float v = us[J * 512];
;         constexpr int TLO = (J - 30 > 0) ? J - 30 : 0, THI = (J < 31) ? J : 31;
; #pragma unroll
;         for (int t = TLO; t <= THI; ++t) acc[t] += v * w[J - t];
;         if constexpr (J + 1 < 62) CfLds<J + 1>::run(acc, w, us);
;     }
	v_pk_fma_f32 v[176:177], v[152:153], v[116:117], v[176:177] op_sel:[0,1,0] op_sel_hi:[1,1,1]
	v_pk_fma_f32 v[178:179], v[152:153], v[122:123], v[178:179] op_sel:[0,1,0] op_sel_hi:[1,1,1]
	v_pk_fma_f32 v[180:181], v[152:153], v[126:127], v[180:181] op_sel:[0,1,0] op_sel_hi:[1,1,1]
	v_pk_fma_f32 v[182:183], v[152:153], v[136:137], v[182:183] op_sel:[0,1,0] op_sel_hi:[1,1,1]
	v_pk_fma_f32 v[184:185], v[152:153], v[138:139], v[184:185] op_sel:[0,1,0] op_sel_hi:[1,1,1]
	v_pk_fma_f32 v[186:187], v[152:153], v[140:141], v[186:187] op_sel:[0,1,0] op_sel_hi:[1,1,1]
	v_pk_fma_f32 v[188:189], v[152:153], v[142:143], v[90:91] op_sel:[0,1,1] op_sel_hi:[1,1,1]
	ds_read2st64_b32 v[150:151], v52 offset0:152 offset1:160
	s_waitcnt lgkmcnt(6)
	v_pk_fma_f32 v[176:177], v[154:155], v[114:115], v[176:177] op_sel:[0,0,0] op_sel_hi:[1,0,1]
	v_pk_fma_f32 v[178:179], v[154:155], v[120:121], v[178:179] op_sel:[0,0,0] op_sel_hi:[1,0,1]
	v_pk_fma_f32 v[180:181], v[154:155], v[126:127], v[180:181] op_sel:[0,0,0] op_sel_hi:[1,0,1]
	v_pk_fma_f32 v[182:183], v[154:155], v[136:137], v[182:183] op_sel:[0,0,0] op_sel_hi:[1,0,1]
	v_pk_fma_f32 v[184:185], v[154:155], v[138:139], v[184:185] op_sel:[0,0,0] op_sel_hi:[1,0,1]
	v_pk_fma_f32 v[186:187], v[154:155], v[140:141], v[186:187] op_sel:[0,0,0] op_sel_hi:[1,0,1]
	v_pk_fma_f32 v[188:189], v[154:155], v[142:143], v[188:189] op_sel:[0,0,0] op_sel_hi:[1,0,1]
	ds_read2st64_b32 v[152:153], v52 offset0:160 offset1:168
	s_waitcnt lgkmcnt(6)
	v_pk_fma_f32 v[176:177], v[156:157], v[110:111], v[176:177] op_sel:[0,1,0] op_sel_hi:[1,1,1]
	v_pk_fma_f32 v[178:179], v[156:157], v[116:117], v[178:179] op_sel:[0,1,0] op_sel_hi:[1,1,1]
	v_pk_fma_f32 v[180:181], v[156:157], v[122:123], v[180:181] op_sel:[0,1,0] op_sel_hi:[1,1,1]
	v_pk_fma_f32 v[182:183], v[156:157], v[126:127], v[182:183] op_sel:[0,1,0] op_sel_hi:[1,1,1]
	v_pk_fma_f32 v[184:185], v[156:157], v[136:137], v[184:185] op_sel:[0,1,0] op_sel_hi:[1,1,1]
	v_pk_fma_f32 v[186:187], v[156:157], v[138:139], v[186:187] op_sel:[0,1,0] op_sel_hi:[1,1,1]
	v_pk_fma_f32 v[188:189], v[156:157], v[140:141], v[188:189] op_sel:[0,1,0] op_sel_hi:[1,1,1]
	v_pk_fma_f32 v[190:191], v[156:157], v[142:143], v[90:91] op_sel:[0,1,1] op_sel_hi:[1,1,1]
	ds_read2st64_b32 v[154:155], v52 offset0:168 offset1:176
	s_waitcnt lgkmcnt(6)
	v_pk_fma_f32 v[176:177], v[158:159], v[108:109], v[176:177] op_sel:[0,0,0] op_sel_hi:[1,0,1]
	v_pk_fma_f32 v[178:179], v[158:159], v[114:115], v[178:179] op_sel:[0,0,0] op_sel_hi:[1,0,1]
	v_pk_fma_f32 v[180:181], v[158:159], v[120:121], v[180:181] op_sel:[0,0,0] op_sel_hi:[1,0,1]
	v_pk_fma_f32 v[182:183], v[158:159], v[126:127], v[182:183] op_sel:[0,0,0] op_sel_hi:[1,0,1]
	v_pk_fma_f32 v[184:185], v[158:159], v[136:137], v[184:185] op_sel:[0,0,0] op_sel_hi:[1,0,1]
	v_pk_fma_f32 v[186:187], v[158:159], v[138:139], v[186:187] op_sel:[0,0,0] op_sel_hi:[1,0,1]
	v_pk_fma_f32 v[188:189], v[158:159], v[140:141], v[188:189] op_sel:[0,0,0] op_sel_hi:[1,0,1]
	v_pk_fma_f32 v[190:191], v[158:159], v[142:143], v[190:191] op_sel:[0,0,0] op_sel_hi:[1,0,1]
	ds_read2st64_b32 v[156:157], v52 offset0:176 offset1:184
	s_waitcnt lgkmcnt(6)
	v_pk_fma_f32 v[176:177], v[144:145], v[106:107], v[176:177] op_sel:[0,0,0] op_sel_hi:[1,0,1]
	v_pk_fma_f32 v[178:179], v[144:145], v[110:111], v[178:179] op_sel:[0,1,0] op_sel_hi:[1,1,1]
	v_pk_fma_f32 v[180:181], v[144:145], v[116:117], v[180:181] op_sel:[0,1,0] op_sel_hi:[1,1,1]
	v_pk_fma_f32 v[182:183], v[144:145], v[122:123], v[182:183] op_sel:[0,1,0] op_sel_hi:[1,1,1]
	v_pk_fma_f32 v[184:185], v[144:145], v[126:127], v[184:185] op_sel:[0,1,0] op_sel_hi:[1,1,1]
	v_pk_fma_f32 v[186:187], v[144:145], v[136:137], v[186:187] op_sel:[0,1,0] op_sel_hi:[1,1,1]
	v_pk_fma_f32 v[188:189], v[144:145], v[138:139], v[188:189] op_sel:[0,1,0] op_sel_hi:[1,1,1]
	v_pk_fma_f32 v[190:191], v[144:145], v[140:141], v[190:191] op_sel:[0,1,0] op_sel_hi:[1,1,1]
	v_pk_fma_f32 v[192:193], v[144:145], v[142:143], v[90:91] op_sel:[0,1,1] op_sel_hi:[1,1,1]
	ds_read2st64_b32 v[158:159], v52 offset0:184 offset1:192
	s_waitcnt lgkmcnt(6)
	v_pk_fma_f32 v[176:177], v[146:147], v[104:105], v[176:177] op_sel:[0,1,0] op_sel_hi:[1,1,1]
	v_pk_fma_f32 v[178:179], v[146:147], v[108:109], v[178:179] op_sel:[0,0,0] op_sel_hi:[1,0,1]
	v_pk_fma_f32 v[180:181], v[146:147], v[114:115], v[180:181] op_sel:[0,0,0] op_sel_hi:[1,0,1]
	v_pk_fma_f32 v[182:183], v[146:147], v[120:121], v[182:183] op_sel:[0,0,0] op_sel_hi:[1,0,1]
	v_pk_fma_f32 v[184:185], v[146:147], v[126:127], v[184:185] op_sel:[0,0,0] op_sel_hi:[1,0,1]
	v_pk_fma_f32 v[186:187], v[146:147], v[136:137], v[186:187] op_sel:[0,0,0] op_sel_hi:[1,0,1]
	v_pk_fma_f32 v[188:189], v[146:147], v[138:139], v[188:189] op_sel:[0,0,0] op_sel_hi:[1,0,1]
	v_pk_fma_f32 v[190:191], v[146:147], v[140:141], v[190:191] op_sel:[0,0,0] op_sel_hi:[1,0,1]
	v_pk_fma_f32 v[192:193], v[146:147], v[142:143], v[192:193] op_sel:[0,0,0] op_sel_hi:[1,0,1]
	ds_read2st64_b32 v[144:145], v52 offset0:192 offset1:200
	s_waitcnt lgkmcnt(6)
	v_pk_fma_f32 v[176:177], v[148:149], v[104:105], v[176:177] op_sel:[0,0,0] op_sel_hi:[1,0,1]
	v_pk_fma_f32 v[178:179], v[148:149], v[106:107], v[178:179] op_sel:[0,0,0] op_sel_hi:[1,0,1]
	v_pk_fma_f32 v[180:181], v[148:149], v[110:111], v[180:181] op_sel:[0,1,0] op_sel_hi:[1,1,1]
	v_pk_fma_f32 v[182:183], v[148:149], v[116:117], v[182:183] op_sel:[0,1,0] op_sel_hi:[1,1,1]
	v_pk_fma_f32 v[184:185], v[148:149], v[122:123], v[184:185] op_sel:[0,1,0] op_sel_hi:[1,1,1]
	v_pk_fma_f32 v[186:187], v[148:149], v[126:127], v[186:187] op_sel:[0,1,0] op_sel_hi:[1,1,1]
	v_pk_fma_f32 v[188:189], v[148:149], v[136:137], v[188:189] op_sel:[0,1,0] op_sel_hi:[1,1,1]
	v_pk_fma_f32 v[190:191], v[148:149], v[138:139], v[190:191] op_sel:[0,1,0] op_sel_hi:[1,1,1]
	v_pk_fma_f32 v[192:193], v[148:149], v[140:141], v[192:193] op_sel:[0,1,0] op_sel_hi:[1,1,1]
	v_pk_fma_f32 v[194:195], v[148:149], v[142:143], v[90:91] op_sel:[0,1,1] op_sel_hi:[1,1,1]
	ds_read2st64_b32 v[146:147], v52 offset0:200 offset1:208
	s_waitcnt lgkmcnt(6)
; #define LAS __attribute__((address_space(3)))
;     static __device__ __forceinline__ void run(float (&acc)[32], const float (&w)[31], const LAS float* us) {
;         const float v = us[J * 512];
;         constexpr int TLO = (J - 30 > 0) ? J - 30 : 0, THI = (J < 31) ? J : 31;
; #pragma unroll
;         for (int t = TLO; t <= THI; ++t) acc[t] += v * w[J - t];
;         if constexpr (J + 1 < 62) CfLds<J + 1>::run(acc, w, us);
;     }
	v_pk_fma_f32 v[176:177], v[150:151], v[102:103], v[176:177] op_sel:[0,1,0] op_sel_hi:[1,1,1]
	v_pk_fma_f32 v[178:179], v[150:151], v[104:105], v[178:179] op_sel:[0,1,0] op_sel_hi:[1,1,1]
	v_pk_fma_f32 v[180:181], v[150:151], v[108:109], v[180:181] op_sel:[0,0,0] op_sel_hi:[1,0,1]
	v_pk_fma_f32 v[182:183], v[150:151], v[114:115], v[182:183] op_sel:[0,0,0] op_sel_hi:[1,0,1]
	v_pk_fma_f32 v[184:185], v[150:151], v[120:121], v[184:185] op_sel:[0,0,0] op_sel_hi:[1,0,1]
	v_pk_fma_f32 v[186:187], v[150:151], v[126:127], v[186:187] op_sel:[0,0,0] op_sel_hi:[1,0,1]
	v_pk_fma_f32 v[188:189], v[150:151], v[136:137], v[188:189] op_sel:[0,0,0] op_sel_hi:[1,0,1]
	v_pk_fma_f32 v[190:191], v[150:151], v[138:139], v[190:191] op_sel:[0,0,0] op_sel_hi:[1,0,1]
	v_pk_fma_f32 v[192:193], v[150:151], v[140:141], v[192:193] op_sel:[0,0,0] op_sel_hi:[1,0,1]
	v_pk_fma_f32 v[194:195], v[150:151], v[142:143], v[194:195] op_sel:[0,0,0] op_sel_hi:[1,0,1]
	ds_read2st64_b32 v[148:149], v52 offset0:208 offset1:216
	s_waitcnt lgkmcnt(6)
	v_pk_fma_f32 v[176:177], v[152:153], v[102:103], v[176:177] op_sel:[0,0,0] op_sel_hi:[1,0,1]
	v_pk_fma_f32 v[178:179], v[152:153], v[104:105], v[178:179] op_sel:[0,0,0] op_sel_hi:[1,0,1]
	v_pk_fma_f32 v[180:181], v[152:153], v[106:107], v[180:181] op_sel:[0,0,0] op_sel_hi:[1,0,1]
	v_pk_fma_f32 v[182:183], v[152:153], v[110:111], v[182:183] op_sel:[0,1,0] op_sel_hi:[1,1,1]
	v_pk_fma_f32 v[184:185], v[152:153], v[116:117], v[184:185] op_sel:[0,1,0] op_sel_hi:[1,1,1]
	v_pk_fma_f32 v[186:187], v[152:153], v[122:123], v[186:187] op_sel:[0,1,0] op_sel_hi:[1,1,1]
	v_pk_fma_f32 v[188:189], v[152:153], v[126:127], v[188:189] op_sel:[0,1,0] op_sel_hi:[1,1,1]
	v_pk_fma_f32 v[190:191], v[152:153], v[136:137], v[190:191] op_sel:[0,1,0] op_sel_hi:[1,1,1]
	v_pk_fma_f32 v[192:193], v[152:153], v[138:139], v[192:193] op_sel:[0,1,0] op_sel_hi:[1,1,1]
	v_pk_fma_f32 v[194:195], v[152:153], v[140:141], v[194:195] op_sel:[0,1,0] op_sel_hi:[1,1,1]
	v_pk_fma_f32 v[196:197], v[152:153], v[142:143], v[90:91] op_sel:[0,1,1] op_sel_hi:[1,1,1]
	ds_read2st64_b32 v[150:151], v52 offset0:216 offset1:224
	s_waitcnt lgkmcnt(6)
	v_pk_fma_f32 v[176:177], v[154:155], v[100:101], v[176:177] op_sel:[0,1,0] op_sel_hi:[1,1,1]
	v_pk_fma_f32 v[178:179], v[154:155], v[102:103], v[178:179] op_sel:[0,1,0] op_sel_hi:[1,1,1]
	v_pk_fma_f32 v[180:181], v[154:155], v[104:105], v[180:181] op_sel:[0,1,0] op_sel_hi:[1,1,1]
	v_pk_fma_f32 v[182:183], v[154:155], v[108:109], v[182:183] op_sel:[0,0,0] op_sel_hi:[1,0,1]
	v_pk_fma_f32 v[184:185], v[154:155], v[114:115], v[184:185] op_sel:[0,0,0] op_sel_hi:[1,0,1]
	v_pk_fma_f32 v[186:187], v[154:155], v[120:121], v[186:187] op_sel:[0,0,0] op_sel_hi:[1,0,1]
	v_pk_fma_f32 v[188:189], v[154:155], v[126:127], v[188:189] op_sel:[0,0,0] op_sel_hi:[1,0,1]
	v_pk_fma_f32 v[190:191], v[154:155], v[136:137], v[190:191] op_sel:[0,0,0] op_sel_hi:[1,0,1]
	v_pk_fma_f32 v[192:193], v[154:155], v[138:139], v[192:193] op_sel:[0,0,0] op_sel_hi:[1,0,1]
	v_pk_fma_f32 v[194:195], v[154:155], v[140:141], v[194:195] op_sel:[0,0,0] op_sel_hi:[1,0,1]
	v_pk_fma_f32 v[196:197], v[154:155], v[142:143], v[196:197] op_sel:[0,0,0] op_sel_hi:[1,0,1]
	ds_read2st64_b32 v[152:153], v52 offset0:224 offset1:232
	s_waitcnt lgkmcnt(6)
	v_pk_fma_f32 v[176:177], v[156:157], v[100:101], v[176:177] op_sel:[0,0,0] op_sel_hi:[1,0,1]
	v_pk_fma_f32 v[178:179], v[156:157], v[102:103], v[178:179] op_sel:[0,0,0] op_sel_hi:[1,0,1]
	v_pk_fma_f32 v[180:181], v[156:157], v[104:105], v[180:181] op_sel:[0,0,0] op_sel_hi:[1,0,1]
	v_pk_fma_f32 v[182:183], v[156:157], v[106:107], v[182:183] op_sel:[0,0,0] op_sel_hi:[1,0,1]
	v_pk_fma_f32 v[184:185], v[156:157], v[110:111], v[184:185] op_sel:[0,1,0] op_sel_hi:[1,1,1]
	v_pk_fma_f32 v[186:187], v[156:157], v[116:117], v[186:187] op_sel:[0,1,0] op_sel_hi:[1,1,1]
	v_pk_fma_f32 v[188:189], v[156:157], v[122:123], v[188:189] op_sel:[0,1,0] op_sel_hi:[1,1,1]
	v_pk_fma_f32 v[190:191], v[156:157], v[126:127], v[190:191] op_sel:[0,1,0] op_sel_hi:[1,1,1]
	v_pk_fma_f32 v[192:193], v[156:157], v[136:137], v[192:193] op_sel:[0,1,0] op_sel_hi:[1,1,1]
	v_pk_fma_f32 v[194:195], v[156:157], v[138:139], v[194:195] op_sel:[0,1,0] op_sel_hi:[1,1,1]
	v_pk_fma_f32 v[196:197], v[156:157], v[140:141], v[196:197] op_sel:[0,1,0] op_sel_hi:[1,1,1]
	v_pk_fma_f32 v[198:199], v[156:157], v[142:143], v[90:91] op_sel:[0,1,1] op_sel_hi:[1,1,1]
	ds_read2st64_b32 v[154:155], v52 offset0:232 offset1:240
	s_waitcnt lgkmcnt(6)
	v_pk_fma_f32 v[176:177], v[158:159], v[98:99], v[176:177] op_sel:[0,1,0] op_sel_hi:[1,1,1]
	v_pk_fma_f32 v[178:179], v[158:159], v[100:101], v[178:179] op_sel:[0,1,0] op_sel_hi:[1,1,1]
	v_pk_fma_f32 v[180:181], v[158:159], v[102:103], v[180:181] op_sel:[0,1,0] op_sel_hi:[1,1,1]
	v_pk_fma_f32 v[182:183], v[158:159], v[104:105], v[182:183] op_sel:[0,1,0] op_sel_hi:[1,1,1]
	v_pk_fma_f32 v[184:185], v[158:159], v[108:109], v[184:185] op_sel:[0,0,0] op_sel_hi:[1,0,1]
	v_pk_fma_f32 v[186:187], v[158:159], v[114:115], v[186:187] op_sel:[0,0,0] op_sel_hi:[1,0,1]
	v_pk_fma_f32 v[188:189], v[158:159], v[120:121], v[188:189] op_sel:[0,0,0] op_sel_hi:[1,0,1]
	v_pk_fma_f32 v[190:191], v[158:159], v[126:127], v[190:191] op_sel:[0,0,0] op_sel_hi:[1,0,1]
	v_pk_fma_f32 v[192:193], v[158:159], v[136:137], v[192:193] op_sel:[0,0,0] op_sel_hi:[1,0,1]
	v_pk_fma_f32 v[194:195], v[158:159], v[138:139], v[194:195] op_sel:[0,0,0] op_sel_hi:[1,0,1]
	v_pk_fma_f32 v[196:197], v[158:159], v[140:141], v[196:197] op_sel:[0,0,0] op_sel_hi:[1,0,1]
	v_pk_fma_f32 v[198:199], v[158:159], v[142:143], v[198:199] op_sel:[0,0,0] op_sel_hi:[1,0,1]
	ds_read2st64_b32 v[156:157], v52 offset0:240 offset1:248
	s_waitcnt lgkmcnt(6)
; #define LAS __attribute__((address_space(3)))
;     static __device__ __forceinline__ void run(float (&acc)[32], const float (&w)[31], const LAS float* us) {
;         const float v = us[J * 512];
;         constexpr int TLO = (J - 30 > 0) ? J - 30 : 0, THI = (J < 31) ? J : 31;
; #pragma unroll
;         for (int t = TLO; t <= THI; ++t) acc[t] += v * w[J - t];
;         if constexpr (J + 1 < 62) CfLds<J + 1>::run(acc, w, us);
;     }
	v_pk_fma_f32 v[176:177], v[144:145], v[98:99], v[176:177] op_sel:[0,0,0] op_sel_hi:[1,0,1]
	v_pk_fma_f32 v[178:179], v[144:145], v[100:101], v[178:179] op_sel:[0,0,0] op_sel_hi:[1,0,1]
	v_pk_fma_f32 v[180:181], v[144:145], v[102:103], v[180:181] op_sel:[0,0,0] op_sel_hi:[1,0,1]
	v_pk_fma_f32 v[182:183], v[144:145], v[104:105], v[182:183] op_sel:[0,0,0] op_sel_hi:[1,0,1]
	v_pk_fma_f32 v[184:185], v[144:145], v[106:107], v[184:185] op_sel:[0,0,0] op_sel_hi:[1,0,1]
	v_pk_fma_f32 v[186:187], v[144:145], v[110:111], v[186:187] op_sel:[0,1,0] op_sel_hi:[1,1,1]
	v_pk_fma_f32 v[188:189], v[144:145], v[116:117], v[188:189] op_sel:[0,1,0] op_sel_hi:[1,1,1]
	v_pk_fma_f32 v[190:191], v[144:145], v[122:123], v[190:191] op_sel:[0,1,0] op_sel_hi:[1,1,1]
	v_pk_fma_f32 v[192:193], v[144:145], v[126:127], v[192:193] op_sel:[0,1,0] op_sel_hi:[1,1,1]
	v_pk_fma_f32 v[194:195], v[144:145], v[136:137], v[194:195] op_sel:[0,1,0] op_sel_hi:[1,1,1]
	v_pk_fma_f32 v[196:197], v[144:145], v[138:139], v[196:197] op_sel:[0,1,0] op_sel_hi:[1,1,1]
	v_pk_fma_f32 v[198:199], v[144:145], v[140:141], v[198:199] op_sel:[0,1,0] op_sel_hi:[1,1,1]
	v_pk_fma_f32 v[200:201], v[144:145], v[142:143], v[90:91] op_sel:[0,1,1] op_sel_hi:[1,1,1]
	ds_read2st64_b32 v[158:159], v160 offset0:120 offset1:128
	s_waitcnt lgkmcnt(6)
	v_pk_fma_f32 v[176:177], v[146:147], v[96:97], v[176:177] op_sel:[0,1,0] op_sel_hi:[1,1,1]
	v_pk_fma_f32 v[178:179], v[146:147], v[98:99], v[178:179] op_sel:[0,1,0] op_sel_hi:[1,1,1]
	v_pk_fma_f32 v[180:181], v[146:147], v[100:101], v[180:181] op_sel:[0,1,0] op_sel_hi:[1,1,1]
	v_pk_fma_f32 v[182:183], v[146:147], v[102:103], v[182:183] op_sel:[0,1,0] op_sel_hi:[1,1,1]
	v_pk_fma_f32 v[184:185], v[146:147], v[104:105], v[184:185] op_sel:[0,1,0] op_sel_hi:[1,1,1]
	v_pk_fma_f32 v[186:187], v[146:147], v[108:109], v[186:187] op_sel:[0,0,0] op_sel_hi:[1,0,1]
	v_pk_fma_f32 v[188:189], v[146:147], v[114:115], v[188:189] op_sel:[0,0,0] op_sel_hi:[1,0,1]
	v_pk_fma_f32 v[190:191], v[146:147], v[120:121], v[190:191] op_sel:[0,0,0] op_sel_hi:[1,0,1]
	v_pk_fma_f32 v[192:193], v[146:147], v[126:127], v[192:193] op_sel:[0,0,0] op_sel_hi:[1,0,1]
	v_pk_fma_f32 v[194:195], v[146:147], v[136:137], v[194:195] op_sel:[0,0,0] op_sel_hi:[1,0,1]
	v_pk_fma_f32 v[196:197], v[146:147], v[138:139], v[196:197] op_sel:[0,0,0] op_sel_hi:[1,0,1]
	v_pk_fma_f32 v[198:199], v[146:147], v[140:141], v[198:199] op_sel:[0,0,0] op_sel_hi:[1,0,1]
	v_pk_fma_f32 v[200:201], v[146:147], v[142:143], v[200:201] op_sel:[0,0,0] op_sel_hi:[1,0,1]
	ds_read2st64_b32 v[144:145], v53 offset0:0 offset1:8
	s_waitcnt lgkmcnt(6)
	v_pk_fma_f32 v[176:177], v[148:149], v[96:97], v[176:177] op_sel:[0,0,0] op_sel_hi:[1,0,1]
	v_pk_fma_f32 v[178:179], v[148:149], v[98:99], v[178:179] op_sel:[0,0,0] op_sel_hi:[1,0,1]
	v_pk_fma_f32 v[180:181], v[148:149], v[100:101], v[180:181] op_sel:[0,0,0] op_sel_hi:[1,0,1]
	v_pk_fma_f32 v[182:183], v[148:149], v[102:103], v[182:183] op_sel:[0,0,0] op_sel_hi:[1,0,1]
	v_pk_fma_f32 v[184:185], v[148:149], v[104:105], v[184:185] op_sel:[0,0,0] op_sel_hi:[1,0,1]
	v_pk_fma_f32 v[186:187], v[148:149], v[106:107], v[186:187] op_sel:[0,0,0] op_sel_hi:[1,0,1]
	v_pk_fma_f32 v[188:189], v[148:149], v[110:111], v[188:189] op_sel:[0,1,0] op_sel_hi:[1,1,1]
	v_pk_fma_f32 v[190:191], v[148:149], v[116:117], v[190:191] op_sel:[0,1,0] op_sel_hi:[1,1,1]
	v_pk_fma_f32 v[192:193], v[148:149], v[122:123], v[192:193] op_sel:[0,1,0] op_sel_hi:[1,1,1]
	v_pk_fma_f32 v[194:195], v[148:149], v[126:127], v[194:195] op_sel:[0,1,0] op_sel_hi:[1,1,1]
	v_pk_fma_f32 v[196:197], v[148:149], v[136:137], v[196:197] op_sel:[0,1,0] op_sel_hi:[1,1,1]
	v_pk_fma_f32 v[198:199], v[148:149], v[138:139], v[198:199] op_sel:[0,1,0] op_sel_hi:[1,1,1]
	v_pk_fma_f32 v[200:201], v[148:149], v[140:141], v[200:201] op_sel:[0,1,0] op_sel_hi:[1,1,1]
	v_pk_fma_f32 v[202:203], v[148:149], v[142:143], v[90:91] op_sel:[0,1,1] op_sel_hi:[1,1,1]
	ds_read2st64_b32 v[146:147], v53 offset0:8 offset1:16
	s_waitcnt lgkmcnt(6)
	v_pk_fma_f32 v[176:177], v[150:151], v[94:95], v[176:177] op_sel:[0,1,0] op_sel_hi:[1,1,1]
	v_pk_fma_f32 v[178:179], v[150:151], v[96:97], v[178:179] op_sel:[0,1,0] op_sel_hi:[1,1,1]
	v_pk_fma_f32 v[180:181], v[150:151], v[98:99], v[180:181] op_sel:[0,1,0] op_sel_hi:[1,1,1]
	v_pk_fma_f32 v[182:183], v[150:151], v[100:101], v[182:183] op_sel:[0,1,0] op_sel_hi:[1,1,1]
	v_pk_fma_f32 v[184:185], v[150:151], v[102:103], v[184:185] op_sel:[0,1,0] op_sel_hi:[1,1,1]
	v_pk_fma_f32 v[186:187], v[150:151], v[104:105], v[186:187] op_sel:[0,1,0] op_sel_hi:[1,1,1]
	v_pk_fma_f32 v[188:189], v[150:151], v[108:109], v[188:189] op_sel:[0,0,0] op_sel_hi:[1,0,1]
	v_pk_fma_f32 v[190:191], v[150:151], v[114:115], v[190:191] op_sel:[0,0,0] op_sel_hi:[1,0,1]
	v_pk_fma_f32 v[192:193], v[150:151], v[120:121], v[192:193] op_sel:[0,0,0] op_sel_hi:[1,0,1]
	v_pk_fma_f32 v[194:195], v[150:151], v[126:127], v[194:195] op_sel:[0,0,0] op_sel_hi:[1,0,1]
	v_pk_fma_f32 v[196:197], v[150:151], v[136:137], v[196:197] op_sel:[0,0,0] op_sel_hi:[1,0,1]
	v_pk_fma_f32 v[198:199], v[150:151], v[138:139], v[198:199] op_sel:[0,0,0] op_sel_hi:[1,0,1]
	v_pk_fma_f32 v[200:201], v[150:151], v[140:141], v[200:201] op_sel:[0,0,0] op_sel_hi:[1,0,1]
	v_pk_fma_f32 v[202:203], v[150:151], v[142:143], v[202:203] op_sel:[0,0,0] op_sel_hi:[1,0,1]
	ds_read2st64_b32 v[148:149], v53 offset0:16 offset1:24
	s_waitcnt lgkmcnt(6)
; #define LAS __attribute__((address_space(3)))
;     static __device__ __forceinline__ void run(float (&acc)[32], const float (&w)[31], const LAS float* us) {
;         const float v = us[J * 512];
;         constexpr int TLO = (J - 30 > 0) ? J - 30 : 0, THI = (J < 31) ? J : 31;
; #pragma unroll
;         for (int t = TLO; t <= THI; ++t) acc[t] += v * w[J - t];
;         if constexpr (J + 1 < 62) CfLds<J + 1>::run(acc, w, us);
;     }
	v_pk_fma_f32 v[176:177], v[152:153], v[94:95], v[176:177] op_sel:[0,0,0] op_sel_hi:[1,0,1]
	v_pk_fma_f32 v[178:179], v[152:153], v[96:97], v[178:179] op_sel:[0,0,0] op_sel_hi:[1,0,1]
	v_pk_fma_f32 v[180:181], v[152:153], v[98:99], v[180:181] op_sel:[0,0,0] op_sel_hi:[1,0,1]
	v_pk_fma_f32 v[182:183], v[152:153], v[100:101], v[182:183] op_sel:[0,0,0] op_sel_hi:[1,0,1]
	v_pk_fma_f32 v[184:185], v[152:153], v[102:103], v[184:185] op_sel:[0,0,0] op_sel_hi:[1,0,1]
	v_pk_fma_f32 v[186:187], v[152:153], v[104:105], v[186:187] op_sel:[0,0,0] op_sel_hi:[1,0,1]
	v_pk_fma_f32 v[188:189], v[152:153], v[106:107], v[188:189] op_sel:[0,0,0] op_sel_hi:[1,0,1]
	v_pk_fma_f32 v[190:191], v[152:153], v[110:111], v[190:191] op_sel:[0,1,0] op_sel_hi:[1,1,1]
	v_pk_fma_f32 v[192:193], v[152:153], v[116:117], v[192:193] op_sel:[0,1,0] op_sel_hi:[1,1,1]
	v_pk_fma_f32 v[194:195], v[152:153], v[122:123], v[194:195] op_sel:[0,1,0] op_sel_hi:[1,1,1]
	v_pk_fma_f32 v[196:197], v[152:153], v[126:127], v[196:197] op_sel:[0,1,0] op_sel_hi:[1,1,1]
	v_pk_fma_f32 v[198:199], v[152:153], v[136:137], v[198:199] op_sel:[0,1,0] op_sel_hi:[1,1,1]
	v_pk_fma_f32 v[200:201], v[152:153], v[138:139], v[200:201] op_sel:[0,1,0] op_sel_hi:[1,1,1]
	v_pk_fma_f32 v[202:203], v[152:153], v[140:141], v[202:203] op_sel:[0,1,0] op_sel_hi:[1,1,1]
	v_pk_fma_f32 v[204:205], v[152:153], v[142:143], v[90:91] op_sel:[0,1,1] op_sel_hi:[1,1,1]
	ds_read2st64_b32 v[150:151], v53 offset0:24 offset1:32
	s_waitcnt lgkmcnt(6)
	v_pk_fma_f32 v[176:177], v[154:155], v[92:93], v[176:177] op_sel:[0,1,0] op_sel_hi:[1,1,1]
	v_pk_fma_f32 v[178:179], v[154:155], v[94:95], v[178:179] op_sel:[0,1,0] op_sel_hi:[1,1,1]
	v_pk_fma_f32 v[180:181], v[154:155], v[96:97], v[180:181] op_sel:[0,1,0] op_sel_hi:[1,1,1]
	v_pk_fma_f32 v[182:183], v[154:155], v[98:99], v[182:183] op_sel:[0,1,0] op_sel_hi:[1,1,1]
	v_pk_fma_f32 v[184:185], v[154:155], v[100:101], v[184:185] op_sel:[0,1,0] op_sel_hi:[1,1,1]
	v_pk_fma_f32 v[186:187], v[154:155], v[102:103], v[186:187] op_sel:[0,1,0] op_sel_hi:[1,1,1]
	v_pk_fma_f32 v[188:189], v[154:155], v[104:105], v[188:189] op_sel:[0,1,0] op_sel_hi:[1,1,1]
	v_pk_fma_f32 v[190:191], v[154:155], v[108:109], v[190:191] op_sel:[0,0,0] op_sel_hi:[1,0,1]
	v_pk_fma_f32 v[192:193], v[154:155], v[114:115], v[192:193] op_sel:[0,0,0] op_sel_hi:[1,0,1]
	v_pk_fma_f32 v[194:195], v[154:155], v[120:121], v[194:195] op_sel:[0,0,0] op_sel_hi:[1,0,1]
	v_pk_fma_f32 v[196:197], v[154:155], v[126:127], v[196:197] op_sel:[0,0,0] op_sel_hi:[1,0,1]
	v_pk_fma_f32 v[198:199], v[154:155], v[136:137], v[198:199] op_sel:[0,0,0] op_sel_hi:[1,0,1]
	v_pk_fma_f32 v[200:201], v[154:155], v[138:139], v[200:201] op_sel:[0,0,0] op_sel_hi:[1,0,1]
	v_pk_fma_f32 v[202:203], v[154:155], v[140:141], v[202:203] op_sel:[0,0,0] op_sel_hi:[1,0,1]
	v_pk_fma_f32 v[204:205], v[154:155], v[142:143], v[204:205] op_sel:[0,0,0] op_sel_hi:[1,0,1]
	ds_read2st64_b32 v[152:153], v53 offset0:32 offset1:40
	s_waitcnt lgkmcnt(6)
	v_pk_fma_f32 v[176:177], v[156:157], v[92:93], v[176:177] op_sel:[0,0,0] op_sel_hi:[1,0,1]
	v_pk_fma_f32 v[178:179], v[156:157], v[94:95], v[178:179] op_sel:[0,0,0] op_sel_hi:[1,0,1]
	v_pk_fma_f32 v[180:181], v[156:157], v[96:97], v[180:181] op_sel:[0,0,0] op_sel_hi:[1,0,1]
	v_pk_fma_f32 v[182:183], v[156:157], v[98:99], v[182:183] op_sel:[0,0,0] op_sel_hi:[1,0,1]
	v_pk_fma_f32 v[184:185], v[156:157], v[100:101], v[184:185] op_sel:[0,0,0] op_sel_hi:[1,0,1]
	v_pk_fma_f32 v[186:187], v[156:157], v[102:103], v[186:187] op_sel:[0,0,0] op_sel_hi:[1,0,1]
	v_pk_fma_f32 v[188:189], v[156:157], v[104:105], v[188:189] op_sel:[0,0,0] op_sel_hi:[1,0,1]
	v_pk_fma_f32 v[190:191], v[156:157], v[106:107], v[190:191] op_sel:[0,0,0] op_sel_hi:[1,0,1]
	v_pk_fma_f32 v[192:193], v[156:157], v[110:111], v[192:193] op_sel:[0,1,0] op_sel_hi:[1,1,1]
	v_pk_fma_f32 v[194:195], v[156:157], v[116:117], v[194:195] op_sel:[0,1,0] op_sel_hi:[1,1,1]
	v_pk_fma_f32 v[196:197], v[156:157], v[122:123], v[196:197] op_sel:[0,1,0] op_sel_hi:[1,1,1]
	v_pk_fma_f32 v[198:199], v[156:157], v[126:127], v[198:199] op_sel:[0,1,0] op_sel_hi:[1,1,1]
	v_pk_fma_f32 v[200:201], v[156:157], v[136:137], v[200:201] op_sel:[0,1,0] op_sel_hi:[1,1,1]
	v_pk_fma_f32 v[202:203], v[156:157], v[138:139], v[202:203] op_sel:[0,1,0] op_sel_hi:[1,1,1]
	v_pk_fma_f32 v[204:205], v[156:157], v[140:141], v[204:205] op_sel:[0,1,0] op_sel_hi:[1,1,1]
	v_pk_fma_f32 v[206:207], v[156:157], v[142:143], v[90:91] op_sel:[0,1,1] op_sel_hi:[1,1,1]
	ds_read2st64_b32 v[154:155], v53 offset0:40 offset1:48
	s_waitcnt lgkmcnt(6)
	v_pk_fma_f32 v[178:179], v[158:159], v[92:93], v[178:179] op_sel:[0,1,0] op_sel_hi:[1,1,1]
	v_pk_fma_f32 v[180:181], v[158:159], v[94:95], v[180:181] op_sel:[0,1,0] op_sel_hi:[1,1,1]
	v_pk_fma_f32 v[182:183], v[158:159], v[96:97], v[182:183] op_sel:[0,1,0] op_sel_hi:[1,1,1]
	v_pk_fma_f32 v[184:185], v[158:159], v[98:99], v[184:185] op_sel:[0,1,0] op_sel_hi:[1,1,1]
	v_pk_fma_f32 v[186:187], v[158:159], v[100:101], v[186:187] op_sel:[0,1,0] op_sel_hi:[1,1,1]
	v_pk_fma_f32 v[188:189], v[158:159], v[102:103], v[188:189] op_sel:[0,1,0] op_sel_hi:[1,1,1]
	v_pk_fma_f32 v[190:191], v[158:159], v[104:105], v[190:191] op_sel:[0,1,0] op_sel_hi:[1,1,1]
	v_pk_fma_f32 v[192:193], v[158:159], v[108:109], v[192:193] op_sel:[0,0,0] op_sel_hi:[1,0,1]
	v_pk_fma_f32 v[194:195], v[158:159], v[114:115], v[194:195] op_sel:[0,0,0] op_sel_hi:[1,0,1]
	v_pk_fma_f32 v[196:197], v[158:159], v[120:121], v[196:197] op_sel:[0,0,0] op_sel_hi:[1,0,1]
	v_pk_fma_f32 v[198:199], v[158:159], v[126:127], v[198:199] op_sel:[0,0,0] op_sel_hi:[1,0,1]
	v_pk_fma_f32 v[200:201], v[158:159], v[136:137], v[200:201] op_sel:[0,0,0] op_sel_hi:[1,0,1]
	v_pk_fma_f32 v[202:203], v[158:159], v[138:139], v[202:203] op_sel:[0,0,0] op_sel_hi:[1,0,1]
	v_pk_fma_f32 v[204:205], v[158:159], v[140:141], v[204:205] op_sel:[0,0,0] op_sel_hi:[1,0,1]
	v_pk_fma_f32 v[206:207], v[158:159], v[142:143], v[206:207] op_sel:[0,0,0] op_sel_hi:[1,0,1]
	ds_read2st64_b32 v[156:157], v53 offset0:48 offset1:56
	s_waitcnt lgkmcnt(6)
; #define LAS __attribute__((address_space(3)))
;     static __device__ __forceinline__ void run(float (&acc)[32], const float (&w)[31], const LAS float* us) {
;         const float v = us[J * 512];
;         constexpr int TLO = (J - 30 > 0) ? J - 30 : 0, THI = (J < 31) ? J : 31;
; #pragma unroll
;         for (int t = TLO; t <= THI; ++t) acc[t] += v * w[J - t];
;         if constexpr (J + 1 < 62) CfLds<J + 1>::run(acc, w, us);
;     }
	v_pk_fma_f32 v[178:179], v[144:145], v[92:93], v[178:179] op_sel:[0,0,0] op_sel_hi:[1,0,1]
	v_pk_fma_f32 v[180:181], v[144:145], v[94:95], v[180:181] op_sel:[0,0,0] op_sel_hi:[1,0,1]
	v_pk_fma_f32 v[182:183], v[144:145], v[96:97], v[182:183] op_sel:[0,0,0] op_sel_hi:[1,0,1]
	v_pk_fma_f32 v[184:185], v[144:145], v[98:99], v[184:185] op_sel:[0,0,0] op_sel_hi:[1,0,1]
	v_pk_fma_f32 v[186:187], v[144:145], v[100:101], v[186:187] op_sel:[0,0,0] op_sel_hi:[1,0,1]
	v_pk_fma_f32 v[188:189], v[144:145], v[102:103], v[188:189] op_sel:[0,0,0] op_sel_hi:[1,0,1]
	v_pk_fma_f32 v[190:191], v[144:145], v[104:105], v[190:191] op_sel:[0,0,0] op_sel_hi:[1,0,1]
	v_pk_fma_f32 v[192:193], v[144:145], v[106:107], v[192:193] op_sel:[0,0,0] op_sel_hi:[1,0,1]
	v_pk_fma_f32 v[194:195], v[144:145], v[110:111], v[194:195] op_sel:[0,1,0] op_sel_hi:[1,1,1]
	v_pk_fma_f32 v[196:197], v[144:145], v[116:117], v[196:197] op_sel:[0,1,0] op_sel_hi:[1,1,1]
	v_pk_fma_f32 v[198:199], v[144:145], v[122:123], v[198:199] op_sel:[0,1,0] op_sel_hi:[1,1,1]
	v_pk_fma_f32 v[200:201], v[144:145], v[126:127], v[200:201] op_sel:[0,1,0] op_sel_hi:[1,1,1]
	v_pk_fma_f32 v[202:203], v[144:145], v[136:137], v[202:203] op_sel:[0,1,0] op_sel_hi:[1,1,1]
	v_pk_fma_f32 v[204:205], v[144:145], v[138:139], v[204:205] op_sel:[0,1,0] op_sel_hi:[1,1,1]
	v_pk_fma_f32 v[206:207], v[144:145], v[140:141], v[206:207] op_sel:[0,1,0] op_sel_hi:[1,1,1]
	ds_read2st64_b32 v[158:159], v53 offset0:56 offset1:64
	s_waitcnt lgkmcnt(6)
	v_pk_fma_f32 v[180:181], v[146:147], v[92:93], v[180:181] op_sel:[0,1,0] op_sel_hi:[1,1,1]
	v_pk_fma_f32 v[182:183], v[146:147], v[94:95], v[182:183] op_sel:[0,1,0] op_sel_hi:[1,1,1]
	v_pk_fma_f32 v[184:185], v[146:147], v[96:97], v[184:185] op_sel:[0,1,0] op_sel_hi:[1,1,1]
	v_pk_fma_f32 v[186:187], v[146:147], v[98:99], v[186:187] op_sel:[0,1,0] op_sel_hi:[1,1,1]
	v_pk_fma_f32 v[188:189], v[146:147], v[100:101], v[188:189] op_sel:[0,1,0] op_sel_hi:[1,1,1]
	v_pk_fma_f32 v[190:191], v[146:147], v[102:103], v[190:191] op_sel:[0,1,0] op_sel_hi:[1,1,1]
	v_pk_fma_f32 v[192:193], v[146:147], v[104:105], v[192:193] op_sel:[0,1,0] op_sel_hi:[1,1,1]
	v_pk_fma_f32 v[194:195], v[146:147], v[108:109], v[194:195] op_sel:[0,0,0] op_sel_hi:[1,0,1]
	v_pk_fma_f32 v[196:197], v[146:147], v[114:115], v[196:197] op_sel:[0,0,0] op_sel_hi:[1,0,1]
	v_pk_fma_f32 v[198:199], v[146:147], v[120:121], v[198:199] op_sel:[0,0,0] op_sel_hi:[1,0,1]
	v_pk_fma_f32 v[200:201], v[146:147], v[126:127], v[200:201] op_sel:[0,0,0] op_sel_hi:[1,0,1]
	v_pk_fma_f32 v[202:203], v[146:147], v[136:137], v[202:203] op_sel:[0,0,0] op_sel_hi:[1,0,1]
	v_pk_fma_f32 v[204:205], v[146:147], v[138:139], v[204:205] op_sel:[0,0,0] op_sel_hi:[1,0,1]
	v_pk_fma_f32 v[206:207], v[146:147], v[140:141], v[206:207] op_sel:[0,0,0] op_sel_hi:[1,0,1]
	ds_read2st64_b32 v[144:145], v53 offset0:64 offset1:72
	s_waitcnt lgkmcnt(6)
	v_pk_fma_f32 v[180:181], v[148:149], v[92:93], v[180:181] op_sel:[0,0,0] op_sel_hi:[1,0,1]
	v_pk_fma_f32 v[182:183], v[148:149], v[94:95], v[182:183] op_sel:[0,0,0] op_sel_hi:[1,0,1]
	v_pk_fma_f32 v[184:185], v[148:149], v[96:97], v[184:185] op_sel:[0,0,0] op_sel_hi:[1,0,1]
	v_pk_fma_f32 v[186:187], v[148:149], v[98:99], v[186:187] op_sel:[0,0,0] op_sel_hi:[1,0,1]
	v_pk_fma_f32 v[188:189], v[148:149], v[100:101], v[188:189] op_sel:[0,0,0] op_sel_hi:[1,0,1]
	v_pk_fma_f32 v[190:191], v[148:149], v[102:103], v[190:191] op_sel:[0,0,0] op_sel_hi:[1,0,1]
	v_pk_fma_f32 v[192:193], v[148:149], v[104:105], v[192:193] op_sel:[0,0,0] op_sel_hi:[1,0,1]
	v_pk_fma_f32 v[194:195], v[148:149], v[106:107], v[194:195] op_sel:[0,0,0] op_sel_hi:[1,0,1]
	v_pk_fma_f32 v[196:197], v[148:149], v[110:111], v[196:197] op_sel:[0,1,0] op_sel_hi:[1,1,1]
	v_pk_fma_f32 v[198:199], v[148:149], v[116:117], v[198:199] op_sel:[0,1,0] op_sel_hi:[1,1,1]
	v_pk_fma_f32 v[200:201], v[148:149], v[122:123], v[200:201] op_sel:[0,1,0] op_sel_hi:[1,1,1]
	v_pk_fma_f32 v[202:203], v[148:149], v[126:127], v[202:203] op_sel:[0,1,0] op_sel_hi:[1,1,1]
	v_pk_fma_f32 v[204:205], v[148:149], v[136:137], v[204:205] op_sel:[0,1,0] op_sel_hi:[1,1,1]
	v_pk_fma_f32 v[206:207], v[148:149], v[138:139], v[206:207] op_sel:[0,1,0] op_sel_hi:[1,1,1]
	ds_read2st64_b32 v[146:147], v53 offset0:72 offset1:80
	s_waitcnt lgkmcnt(6)
	v_pk_fma_f32 v[182:183], v[150:151], v[92:93], v[182:183] op_sel:[0,1,0] op_sel_hi:[1,1,1]
	v_pk_fma_f32 v[184:185], v[150:151], v[94:95], v[184:185] op_sel:[0,1,0] op_sel_hi:[1,1,1]
	v_pk_fma_f32 v[186:187], v[150:151], v[96:97], v[186:187] op_sel:[0,1,0] op_sel_hi:[1,1,1]
	v_pk_fma_f32 v[188:189], v[150:151], v[98:99], v[188:189] op_sel:[0,1,0] op_sel_hi:[1,1,1]
	v_pk_fma_f32 v[190:191], v[150:151], v[100:101], v[190:191] op_sel:[0,1,0] op_sel_hi:[1,1,1]
	v_pk_fma_f32 v[192:193], v[150:151], v[102:103], v[192:193] op_sel:[0,1,0] op_sel_hi:[1,1,1]
	v_pk_fma_f32 v[194:195], v[150:151], v[104:105], v[194:195] op_sel:[0,1,0] op_sel_hi:[1,1,1]
	v_pk_fma_f32 v[196:197], v[150:151], v[108:109], v[196:197] op_sel:[0,0,0] op_sel_hi:[1,0,1]
	v_pk_fma_f32 v[198:199], v[150:151], v[114:115], v[198:199] op_sel:[0,0,0] op_sel_hi:[1,0,1]
	v_pk_fma_f32 v[200:201], v[150:151], v[120:121], v[200:201] op_sel:[0,0,0] op_sel_hi:[1,0,1]
	v_pk_fma_f32 v[202:203], v[150:151], v[126:127], v[202:203] op_sel:[0,0,0] op_sel_hi:[1,0,1]
	v_pk_fma_f32 v[204:205], v[150:151], v[136:137], v[204:205] op_sel:[0,0,0] op_sel_hi:[1,0,1]
	v_pk_fma_f32 v[206:207], v[150:151], v[138:139], v[206:207] op_sel:[0,0,0] op_sel_hi:[1,0,1]
	ds_read2st64_b32 v[148:149], v53 offset0:80 offset1:88
	s_waitcnt lgkmcnt(6)
; #define LAS __attribute__((address_space(3)))
;     static __device__ __forceinline__ void run(float (&acc)[32], const float (&w)[31], const LAS float* us) {
;         const float v = us[J * 512];
;         constexpr int TLO = (J - 30 > 0) ? J - 30 : 0, THI = (J < 31) ? J : 31;
; #pragma unroll
;         for (int t = TLO; t <= THI; ++t) acc[t] += v * w[J - t];
;         if constexpr (J + 1 < 62) CfLds<J + 1>::run(acc, w, us);
;     }
	v_pk_fma_f32 v[182:183], v[152:153], v[92:93], v[182:183] op_sel:[0,0,0] op_sel_hi:[1,0,1]
	v_pk_fma_f32 v[184:185], v[152:153], v[94:95], v[184:185] op_sel:[0,0,0] op_sel_hi:[1,0,1]
	v_pk_fma_f32 v[186:187], v[152:153], v[96:97], v[186:187] op_sel:[0,0,0] op_sel_hi:[1,0,1]
	v_pk_fma_f32 v[188:189], v[152:153], v[98:99], v[188:189] op_sel:[0,0,0] op_sel_hi:[1,0,1]
	v_pk_fma_f32 v[190:191], v[152:153], v[100:101], v[190:191] op_sel:[0,0,0] op_sel_hi:[1,0,1]
	v_pk_fma_f32 v[192:193], v[152:153], v[102:103], v[192:193] op_sel:[0,0,0] op_sel_hi:[1,0,1]
	v_pk_fma_f32 v[194:195], v[152:153], v[104:105], v[194:195] op_sel:[0,0,0] op_sel_hi:[1,0,1]
	v_pk_fma_f32 v[196:197], v[152:153], v[106:107], v[196:197] op_sel:[0,0,0] op_sel_hi:[1,0,1]
	v_pk_fma_f32 v[198:199], v[152:153], v[110:111], v[198:199] op_sel:[0,1,0] op_sel_hi:[1,1,1]
	v_pk_fma_f32 v[200:201], v[152:153], v[116:117], v[200:201] op_sel:[0,1,0] op_sel_hi:[1,1,1]
	v_pk_fma_f32 v[202:203], v[152:153], v[122:123], v[202:203] op_sel:[0,1,0] op_sel_hi:[1,1,1]
	v_pk_fma_f32 v[204:205], v[152:153], v[126:127], v[204:205] op_sel:[0,1,0] op_sel_hi:[1,1,1]
	v_pk_fma_f32 v[206:207], v[152:153], v[136:137], v[206:207] op_sel:[0,1,0] op_sel_hi:[1,1,1]
	ds_read2st64_b32 v[150:151], v53 offset0:88 offset1:96
	s_waitcnt lgkmcnt(6)
	v_pk_fma_f32 v[184:185], v[154:155], v[92:93], v[184:185] op_sel:[0,1,0] op_sel_hi:[1,1,1]
	v_pk_fma_f32 v[186:187], v[154:155], v[94:95], v[186:187] op_sel:[0,1,0] op_sel_hi:[1,1,1]
	v_pk_fma_f32 v[188:189], v[154:155], v[96:97], v[188:189] op_sel:[0,1,0] op_sel_hi:[1,1,1]
	v_pk_fma_f32 v[190:191], v[154:155], v[98:99], v[190:191] op_sel:[0,1,0] op_sel_hi:[1,1,1]
	v_pk_fma_f32 v[192:193], v[154:155], v[100:101], v[192:193] op_sel:[0,1,0] op_sel_hi:[1,1,1]
	v_pk_fma_f32 v[194:195], v[154:155], v[102:103], v[194:195] op_sel:[0,1,0] op_sel_hi:[1,1,1]
	v_pk_fma_f32 v[196:197], v[154:155], v[104:105], v[196:197] op_sel:[0,1,0] op_sel_hi:[1,1,1]
	v_pk_fma_f32 v[198:199], v[154:155], v[108:109], v[198:199] op_sel:[0,0,0] op_sel_hi:[1,0,1]
	v_pk_fma_f32 v[200:201], v[154:155], v[114:115], v[200:201] op_sel:[0,0,0] op_sel_hi:[1,0,1]
	v_pk_fma_f32 v[202:203], v[154:155], v[120:121], v[202:203] op_sel:[0,0,0] op_sel_hi:[1,0,1]
	v_pk_fma_f32 v[204:205], v[154:155], v[126:127], v[204:205] op_sel:[0,0,0] op_sel_hi:[1,0,1]
	v_pk_fma_f32 v[206:207], v[154:155], v[136:137], v[206:207] op_sel:[0,0,0] op_sel_hi:[1,0,1]
	ds_read2st64_b32 v[152:153], v53 offset0:96 offset1:104
	s_waitcnt lgkmcnt(6)
	v_pk_fma_f32 v[184:185], v[156:157], v[92:93], v[184:185] op_sel:[0,0,0] op_sel_hi:[1,0,1]
	v_pk_fma_f32 v[186:187], v[156:157], v[94:95], v[186:187] op_sel:[0,0,0] op_sel_hi:[1,0,1]
	v_pk_fma_f32 v[188:189], v[156:157], v[96:97], v[188:189] op_sel:[0,0,0] op_sel_hi:[1,0,1]
	v_pk_fma_f32 v[190:191], v[156:157], v[98:99], v[190:191] op_sel:[0,0,0] op_sel_hi:[1,0,1]
	v_pk_fma_f32 v[192:193], v[156:157], v[100:101], v[192:193] op_sel:[0,0,0] op_sel_hi:[1,0,1]
	v_pk_fma_f32 v[194:195], v[156:157], v[102:103], v[194:195] op_sel:[0,0,0] op_sel_hi:[1,0,1]
	v_pk_fma_f32 v[196:197], v[156:157], v[104:105], v[196:197] op_sel:[0,0,0] op_sel_hi:[1,0,1]
	v_pk_fma_f32 v[198:199], v[156:157], v[106:107], v[198:199] op_sel:[0,0,0] op_sel_hi:[1,0,1]
	v_pk_fma_f32 v[200:201], v[156:157], v[110:111], v[200:201] op_sel:[0,1,0] op_sel_hi:[1,1,1]
	v_pk_fma_f32 v[202:203], v[156:157], v[116:117], v[202:203] op_sel:[0,1,0] op_sel_hi:[1,1,1]
	v_pk_fma_f32 v[204:205], v[156:157], v[122:123], v[204:205] op_sel:[0,1,0] op_sel_hi:[1,1,1]
	v_pk_fma_f32 v[206:207], v[156:157], v[126:127], v[206:207] op_sel:[0,1,0] op_sel_hi:[1,1,1]
	ds_read2st64_b32 v[154:155], v53 offset0:104 offset1:112
	s_waitcnt lgkmcnt(6)
	v_pk_fma_f32 v[186:187], v[158:159], v[92:93], v[186:187] op_sel:[0,1,0] op_sel_hi:[1,1,1]
	v_pk_fma_f32 v[188:189], v[158:159], v[94:95], v[188:189] op_sel:[0,1,0] op_sel_hi:[1,1,1]
	v_pk_fma_f32 v[190:191], v[158:159], v[96:97], v[190:191] op_sel:[0,1,0] op_sel_hi:[1,1,1]
	v_pk_fma_f32 v[192:193], v[158:159], v[98:99], v[192:193] op_sel:[0,1,0] op_sel_hi:[1,1,1]
	v_pk_fma_f32 v[194:195], v[158:159], v[100:101], v[194:195] op_sel:[0,1,0] op_sel_hi:[1,1,1]
	v_pk_fma_f32 v[196:197], v[158:159], v[102:103], v[196:197] op_sel:[0,1,0] op_sel_hi:[1,1,1]
	v_pk_fma_f32 v[198:199], v[158:159], v[104:105], v[198:199] op_sel:[0,1,0] op_sel_hi:[1,1,1]
	v_pk_fma_f32 v[200:201], v[158:159], v[108:109], v[200:201] op_sel:[0,0,0] op_sel_hi:[1,0,1]
	v_pk_fma_f32 v[202:203], v[158:159], v[114:115], v[202:203] op_sel:[0,0,0] op_sel_hi:[1,0,1]
	v_pk_fma_f32 v[204:205], v[158:159], v[120:121], v[204:205] op_sel:[0,0,0] op_sel_hi:[1,0,1]
	v_pk_fma_f32 v[206:207], v[158:159], v[126:127], v[206:207] op_sel:[0,0,0] op_sel_hi:[1,0,1]
	ds_read2st64_b32 v[156:157], v53 offset0:112 offset1:120
	s_waitcnt lgkmcnt(6)
	v_pk_fma_f32 v[186:187], v[144:145], v[92:93], v[186:187] op_sel:[0,0,0] op_sel_hi:[1,0,1]
	v_pk_fma_f32 v[188:189], v[144:145], v[94:95], v[188:189] op_sel:[0,0,0] op_sel_hi:[1,0,1]
	v_pk_fma_f32 v[190:191], v[144:145], v[96:97], v[190:191] op_sel:[0,0,0] op_sel_hi:[1,0,1]
	v_pk_fma_f32 v[192:193], v[144:145], v[98:99], v[192:193] op_sel:[0,0,0] op_sel_hi:[1,0,1]
	v_pk_fma_f32 v[194:195], v[144:145], v[100:101], v[194:195] op_sel:[0,0,0] op_sel_hi:[1,0,1]
	v_pk_fma_f32 v[196:197], v[144:145], v[102:103], v[196:197] op_sel:[0,0,0] op_sel_hi:[1,0,1]
	v_pk_fma_f32 v[198:199], v[144:145], v[104:105], v[198:199] op_sel:[0,0,0] op_sel_hi:[1,0,1]
	v_pk_fma_f32 v[200:201], v[144:145], v[106:107], v[200:201] op_sel:[0,0,0] op_sel_hi:[1,0,1]
	v_pk_fma_f32 v[202:203], v[144:145], v[110:111], v[202:203] op_sel:[0,1,0] op_sel_hi:[1,1,1]
	v_pk_fma_f32 v[204:205], v[144:145], v[116:117], v[204:205] op_sel:[0,1,0] op_sel_hi:[1,1,1]
	v_pk_fma_f32 v[206:207], v[144:145], v[122:123], v[206:207] op_sel:[0,1,0] op_sel_hi:[1,1,1]
	ds_read2st64_b32 v[158:159], v53 offset0:120 offset1:128
	s_waitcnt lgkmcnt(6)
; #define LAS __attribute__((address_space(3)))
;     static __device__ __forceinline__ void run(float (&acc)[32], const float (&w)[31], const LAS float* us) {
;         const float v = us[J * 512];
;         constexpr int TLO = (J - 30 > 0) ? J - 30 : 0, THI = (J < 31) ? J : 31;
; #pragma unroll
;         for (int t = TLO; t <= THI; ++t) acc[t] += v * w[J - t];
;         if constexpr (J + 1 < 62) CfLds<J + 1>::run(acc, w, us);
;     }
	v_pk_fma_f32 v[188:189], v[146:147], v[92:93], v[188:189] op_sel:[0,1,0] op_sel_hi:[1,1,1]
	v_pk_fma_f32 v[190:191], v[146:147], v[94:95], v[190:191] op_sel:[0,1,0] op_sel_hi:[1,1,1]
	v_pk_fma_f32 v[192:193], v[146:147], v[96:97], v[192:193] op_sel:[0,1,0] op_sel_hi:[1,1,1]
	v_pk_fma_f32 v[194:195], v[146:147], v[98:99], v[194:195] op_sel:[0,1,0] op_sel_hi:[1,1,1]
	v_pk_fma_f32 v[196:197], v[146:147], v[100:101], v[196:197] op_sel:[0,1,0] op_sel_hi:[1,1,1]
	v_pk_fma_f32 v[198:199], v[146:147], v[102:103], v[198:199] op_sel:[0,1,0] op_sel_hi:[1,1,1]
	v_pk_fma_f32 v[200:201], v[146:147], v[104:105], v[200:201] op_sel:[0,1,0] op_sel_hi:[1,1,1]
	v_pk_fma_f32 v[202:203], v[146:147], v[108:109], v[202:203] op_sel:[0,0,0] op_sel_hi:[1,0,1]
	v_pk_fma_f32 v[204:205], v[146:147], v[114:115], v[204:205] op_sel:[0,0,0] op_sel_hi:[1,0,1]
	v_pk_fma_f32 v[206:207], v[146:147], v[120:121], v[206:207] op_sel:[0,0,0] op_sel_hi:[1,0,1]
	ds_read2st64_b32 v[144:145], v53 offset0:128 offset1:136
	s_waitcnt lgkmcnt(6)
	v_pk_fma_f32 v[188:189], v[148:149], v[92:93], v[188:189] op_sel:[0,0,0] op_sel_hi:[1,0,1]
	v_pk_fma_f32 v[190:191], v[148:149], v[94:95], v[190:191] op_sel:[0,0,0] op_sel_hi:[1,0,1]
	v_pk_fma_f32 v[192:193], v[148:149], v[96:97], v[192:193] op_sel:[0,0,0] op_sel_hi:[1,0,1]
	v_pk_fma_f32 v[194:195], v[148:149], v[98:99], v[194:195] op_sel:[0,0,0] op_sel_hi:[1,0,1]
	v_pk_fma_f32 v[196:197], v[148:149], v[100:101], v[196:197] op_sel:[0,0,0] op_sel_hi:[1,0,1]
	v_pk_fma_f32 v[198:199], v[148:149], v[102:103], v[198:199] op_sel:[0,0,0] op_sel_hi:[1,0,1]
	v_pk_fma_f32 v[200:201], v[148:149], v[104:105], v[200:201] op_sel:[0,0,0] op_sel_hi:[1,0,1]
	v_pk_fma_f32 v[202:203], v[148:149], v[106:107], v[202:203] op_sel:[0,0,0] op_sel_hi:[1,0,1]
	v_pk_fma_f32 v[204:205], v[148:149], v[110:111], v[204:205] op_sel:[0,1,0] op_sel_hi:[1,1,1]
	v_pk_fma_f32 v[206:207], v[148:149], v[116:117], v[206:207] op_sel:[0,1,0] op_sel_hi:[1,1,1]
	ds_read2st64_b32 v[146:147], v53 offset0:136 offset1:144
	s_waitcnt lgkmcnt(6)
	v_pk_fma_f32 v[190:191], v[150:151], v[92:93], v[190:191] op_sel:[0,1,0] op_sel_hi:[1,1,1]
	v_pk_fma_f32 v[192:193], v[150:151], v[94:95], v[192:193] op_sel:[0,1,0] op_sel_hi:[1,1,1]
	v_pk_fma_f32 v[194:195], v[150:151], v[96:97], v[194:195] op_sel:[0,1,0] op_sel_hi:[1,1,1]
	v_pk_fma_f32 v[196:197], v[150:151], v[98:99], v[196:197] op_sel:[0,1,0] op_sel_hi:[1,1,1]
	v_pk_fma_f32 v[198:199], v[150:151], v[100:101], v[198:199] op_sel:[0,1,0] op_sel_hi:[1,1,1]
	v_pk_fma_f32 v[200:201], v[150:151], v[102:103], v[200:201] op_sel:[0,1,0] op_sel_hi:[1,1,1]
	v_pk_fma_f32 v[202:203], v[150:151], v[104:105], v[202:203] op_sel:[0,1,0] op_sel_hi:[1,1,1]
	v_pk_fma_f32 v[204:205], v[150:151], v[108:109], v[204:205] op_sel:[0,0,0] op_sel_hi:[1,0,1]
	v_pk_fma_f32 v[206:207], v[150:151], v[114:115], v[206:207] op_sel:[0,0,0] op_sel_hi:[1,0,1]
	ds_read2st64_b32 v[148:149], v53 offset0:144 offset1:152
	s_waitcnt lgkmcnt(6)
	v_pk_fma_f32 v[190:191], v[152:153], v[92:93], v[190:191] op_sel:[0,0,0] op_sel_hi:[1,0,1]
	v_pk_fma_f32 v[192:193], v[152:153], v[94:95], v[192:193] op_sel:[0,0,0] op_sel_hi:[1,0,1]
	v_pk_fma_f32 v[194:195], v[152:153], v[96:97], v[194:195] op_sel:[0,0,0] op_sel_hi:[1,0,1]
	v_pk_fma_f32 v[196:197], v[152:153], v[98:99], v[196:197] op_sel:[0,0,0] op_sel_hi:[1,0,1]
	v_pk_fma_f32 v[198:199], v[152:153], v[100:101], v[198:199] op_sel:[0,0,0] op_sel_hi:[1,0,1]
	v_pk_fma_f32 v[200:201], v[152:153], v[102:103], v[200:201] op_sel:[0,0,0] op_sel_hi:[1,0,1]
	v_pk_fma_f32 v[202:203], v[152:153], v[104:105], v[202:203] op_sel:[0,0,0] op_sel_hi:[1,0,1]
	v_pk_fma_f32 v[204:205], v[152:153], v[106:107], v[204:205] op_sel:[0,0,0] op_sel_hi:[1,0,1]
	v_pk_fma_f32 v[206:207], v[152:153], v[110:111], v[206:207] op_sel:[0,1,0] op_sel_hi:[1,1,1]
	ds_read2st64_b32 v[150:151], v53 offset0:152 offset1:160
	s_waitcnt lgkmcnt(6)
	v_pk_fma_f32 v[192:193], v[154:155], v[92:93], v[192:193] op_sel:[0,1,0] op_sel_hi:[1,1,1]
	v_pk_fma_f32 v[194:195], v[154:155], v[94:95], v[194:195] op_sel:[0,1,0] op_sel_hi:[1,1,1]
	v_pk_fma_f32 v[196:197], v[154:155], v[96:97], v[196:197] op_sel:[0,1,0] op_sel_hi:[1,1,1]
	v_pk_fma_f32 v[198:199], v[154:155], v[98:99], v[198:199] op_sel:[0,1,0] op_sel_hi:[1,1,1]
	v_pk_fma_f32 v[200:201], v[154:155], v[100:101], v[200:201] op_sel:[0,1,0] op_sel_hi:[1,1,1]
	v_pk_fma_f32 v[202:203], v[154:155], v[102:103], v[202:203] op_sel:[0,1,0] op_sel_hi:[1,1,1]
	v_pk_fma_f32 v[204:205], v[154:155], v[104:105], v[204:205] op_sel:[0,1,0] op_sel_hi:[1,1,1]
	v_pk_fma_f32 v[206:207], v[154:155], v[108:109], v[206:207] op_sel:[0,0,0] op_sel_hi:[1,0,1]
	ds_read2st64_b32 v[152:153], v53 offset0:160 offset1:168
	s_waitcnt lgkmcnt(6)
	v_pk_fma_f32 v[192:193], v[156:157], v[92:93], v[192:193] op_sel:[0,0,0] op_sel_hi:[1,0,1]
	v_pk_fma_f32 v[194:195], v[156:157], v[94:95], v[194:195] op_sel:[0,0,0] op_sel_hi:[1,0,1]
	v_pk_fma_f32 v[196:197], v[156:157], v[96:97], v[196:197] op_sel:[0,0,0] op_sel_hi:[1,0,1]
	v_pk_fma_f32 v[198:199], v[156:157], v[98:99], v[198:199] op_sel:[0,0,0] op_sel_hi:[1,0,1]
	v_pk_fma_f32 v[200:201], v[156:157], v[100:101], v[200:201] op_sel:[0,0,0] op_sel_hi:[1,0,1]
	v_pk_fma_f32 v[202:203], v[156:157], v[102:103], v[202:203] op_sel:[0,0,0] op_sel_hi:[1,0,1]
	v_pk_fma_f32 v[204:205], v[156:157], v[104:105], v[204:205] op_sel:[0,0,0] op_sel_hi:[1,0,1]
	v_pk_fma_f32 v[206:207], v[156:157], v[106:107], v[206:207] op_sel:[0,0,0] op_sel_hi:[1,0,1]
	ds_read2st64_b32 v[154:155], v53 offset0:168 offset1:176
	s_waitcnt lgkmcnt(6)
; #define LAS __attribute__((address_space(3)))
;     static __device__ __forceinline__ void run(float (&acc)[32], const float (&w)[31], const LAS float* us) {
;         const float v = us[J * 512];
;         constexpr int TLO = (J - 30 > 0) ? J - 30 : 0, THI = (J < 31) ? J : 31;
; #pragma unroll
;         for (int t = TLO; t <= THI; ++t) acc[t] += v * w[J - t];
;         if constexpr (J + 1 < 62) CfLds<J + 1>::run(acc, w, us);
;     }
	v_pk_fma_f32 v[194:195], v[158:159], v[92:93], v[194:195] op_sel:[0,1,0] op_sel_hi:[1,1,1]
	v_pk_fma_f32 v[196:197], v[158:159], v[94:95], v[196:197] op_sel:[0,1,0] op_sel_hi:[1,1,1]
	v_pk_fma_f32 v[198:199], v[158:159], v[96:97], v[198:199] op_sel:[0,1,0] op_sel_hi:[1,1,1]
	v_pk_fma_f32 v[200:201], v[158:159], v[98:99], v[200:201] op_sel:[0,1,0] op_sel_hi:[1,1,1]
	v_pk_fma_f32 v[202:203], v[158:159], v[100:101], v[202:203] op_sel:[0,1,0] op_sel_hi:[1,1,1]
	v_pk_fma_f32 v[204:205], v[158:159], v[102:103], v[204:205] op_sel:[0,1,0] op_sel_hi:[1,1,1]
	v_pk_fma_f32 v[206:207], v[158:159], v[104:105], v[206:207] op_sel:[0,1,0] op_sel_hi:[1,1,1]
	ds_read2st64_b32 v[156:157], v53 offset0:176 offset1:184
	s_waitcnt lgkmcnt(6)
	v_pk_fma_f32 v[194:195], v[144:145], v[92:93], v[194:195] op_sel:[0,0,0] op_sel_hi:[1,0,1]
	v_pk_fma_f32 v[196:197], v[144:145], v[94:95], v[196:197] op_sel:[0,0,0] op_sel_hi:[1,0,1]
	v_pk_fma_f32 v[198:199], v[144:145], v[96:97], v[198:199] op_sel:[0,0,0] op_sel_hi:[1,0,1]
	v_pk_fma_f32 v[200:201], v[144:145], v[98:99], v[200:201] op_sel:[0,0,0] op_sel_hi:[1,0,1]
	v_pk_fma_f32 v[202:203], v[144:145], v[100:101], v[202:203] op_sel:[0,0,0] op_sel_hi:[1,0,1]
	v_pk_fma_f32 v[204:205], v[144:145], v[102:103], v[204:205] op_sel:[0,0,0] op_sel_hi:[1,0,1]
	v_pk_fma_f32 v[206:207], v[144:145], v[104:105], v[206:207] op_sel:[0,0,0] op_sel_hi:[1,0,1]
	ds_read2st64_b32 v[158:159], v53 offset0:184 offset1:192
	s_waitcnt lgkmcnt(6)
	v_pk_fma_f32 v[196:197], v[146:147], v[92:93], v[196:197] op_sel:[0,1,0] op_sel_hi:[1,1,1]
	v_pk_fma_f32 v[198:199], v[146:147], v[94:95], v[198:199] op_sel:[0,1,0] op_sel_hi:[1,1,1]
	v_pk_fma_f32 v[200:201], v[146:147], v[96:97], v[200:201] op_sel:[0,1,0] op_sel_hi:[1,1,1]
	v_pk_fma_f32 v[202:203], v[146:147], v[98:99], v[202:203] op_sel:[0,1,0] op_sel_hi:[1,1,1]
	v_pk_fma_f32 v[204:205], v[146:147], v[100:101], v[204:205] op_sel:[0,1,0] op_sel_hi:[1,1,1]
	v_pk_fma_f32 v[206:207], v[146:147], v[102:103], v[206:207] op_sel:[0,1,0] op_sel_hi:[1,1,1]
	ds_read2st64_b32 v[144:145], v53 offset0:192 offset1:200
	s_waitcnt lgkmcnt(6)
	v_pk_fma_f32 v[196:197], v[148:149], v[92:93], v[196:197] op_sel:[0,0,0] op_sel_hi:[1,0,1]
	v_pk_fma_f32 v[198:199], v[148:149], v[94:95], v[198:199] op_sel:[0,0,0] op_sel_hi:[1,0,1]
	v_pk_fma_f32 v[200:201], v[148:149], v[96:97], v[200:201] op_sel:[0,0,0] op_sel_hi:[1,0,1]
	v_pk_fma_f32 v[202:203], v[148:149], v[98:99], v[202:203] op_sel:[0,0,0] op_sel_hi:[1,0,1]
	v_pk_fma_f32 v[204:205], v[148:149], v[100:101], v[204:205] op_sel:[0,0,0] op_sel_hi:[1,0,1]
	v_pk_fma_f32 v[206:207], v[148:149], v[102:103], v[206:207] op_sel:[0,0,0] op_sel_hi:[1,0,1]
	ds_read2st64_b32 v[146:147], v53 offset0:200 offset1:208
	s_waitcnt lgkmcnt(6)
	v_pk_fma_f32 v[198:199], v[150:151], v[92:93], v[198:199] op_sel:[0,1,0] op_sel_hi:[1,1,1]
	v_pk_fma_f32 v[200:201], v[150:151], v[94:95], v[200:201] op_sel:[0,1,0] op_sel_hi:[1,1,1]
	v_pk_fma_f32 v[202:203], v[150:151], v[96:97], v[202:203] op_sel:[0,1,0] op_sel_hi:[1,1,1]
	v_pk_fma_f32 v[204:205], v[150:151], v[98:99], v[204:205] op_sel:[0,1,0] op_sel_hi:[1,1,1]
	v_pk_fma_f32 v[206:207], v[150:151], v[100:101], v[206:207] op_sel:[0,1,0] op_sel_hi:[1,1,1]
	ds_read2st64_b32 v[148:149], v53 offset0:208 offset1:216
	s_waitcnt lgkmcnt(6)
	v_pk_fma_f32 v[198:199], v[152:153], v[92:93], v[198:199] op_sel:[0,0,0] op_sel_hi:[1,0,1]
	v_pk_fma_f32 v[200:201], v[152:153], v[94:95], v[200:201] op_sel:[0,0,0] op_sel_hi:[1,0,1]
	v_pk_fma_f32 v[202:203], v[152:153], v[96:97], v[202:203] op_sel:[0,0,0] op_sel_hi:[1,0,1]
	v_pk_fma_f32 v[204:205], v[152:153], v[98:99], v[204:205] op_sel:[0,0,0] op_sel_hi:[1,0,1]
	v_pk_fma_f32 v[206:207], v[152:153], v[100:101], v[206:207] op_sel:[0,0,0] op_sel_hi:[1,0,1]
	ds_read2st64_b32 v[150:151], v53 offset0:216 offset1:224
	s_waitcnt lgkmcnt(6)
	v_pk_fma_f32 v[200:201], v[154:155], v[92:93], v[200:201] op_sel:[0,1,0] op_sel_hi:[1,1,1]
	v_pk_fma_f32 v[202:203], v[154:155], v[94:95], v[202:203] op_sel:[0,1,0] op_sel_hi:[1,1,1]
	v_pk_fma_f32 v[204:205], v[154:155], v[96:97], v[204:205] op_sel:[0,1,0] op_sel_hi:[1,1,1]
	v_pk_fma_f32 v[206:207], v[154:155], v[98:99], v[206:207] op_sel:[0,1,0] op_sel_hi:[1,1,1]
	ds_read2st64_b32 v[152:153], v53 offset0:224 offset1:232
	s_waitcnt lgkmcnt(6)
	v_pk_fma_f32 v[200:201], v[156:157], v[92:93], v[200:201] op_sel:[0,0,0] op_sel_hi:[1,0,1]
	v_pk_fma_f32 v[202:203], v[156:157], v[94:95], v[202:203] op_sel:[0,0,0] op_sel_hi:[1,0,1]
	v_pk_fma_f32 v[204:205], v[156:157], v[96:97], v[204:205] op_sel:[0,0,0] op_sel_hi:[1,0,1]
	v_pk_fma_f32 v[206:207], v[156:157], v[98:99], v[206:207] op_sel:[0,0,0] op_sel_hi:[1,0,1]
	s_waitcnt lgkmcnt(5)
	v_pk_fma_f32 v[202:203], v[158:159], v[92:93], v[202:203] op_sel:[0,1,0] op_sel_hi:[1,1,1]
	v_pk_fma_f32 v[204:205], v[158:159], v[94:95], v[204:205] op_sel:[0,1,0] op_sel_hi:[1,1,1]
	v_pk_fma_f32 v[206:207], v[158:159], v[96:97], v[206:207] op_sel:[0,1,0] op_sel_hi:[1,1,1]
	s_waitcnt lgkmcnt(4)
	v_pk_fma_f32 v[202:203], v[144:145], v[92:93], v[202:203] op_sel:[0,0,0] op_sel_hi:[1,0,1]
	v_pk_fma_f32 v[204:205], v[144:145], v[94:95], v[204:205] op_sel:[0,0,0] op_sel_hi:[1,0,1]
	v_pk_fma_f32 v[206:207], v[144:145], v[96:97], v[206:207] op_sel:[0,0,0] op_sel_hi:[1,0,1]
	s_waitcnt lgkmcnt(3)
	v_pk_fma_f32 v[204:205], v[146:147], v[92:93], v[204:205] op_sel:[0,1,0] op_sel_hi:[1,1,1]
	v_pk_fma_f32 v[206:207], v[146:147], v[94:95], v[206:207] op_sel:[0,1,0] op_sel_hi:[1,1,1]
	s_waitcnt lgkmcnt(2)
	v_pk_fma_f32 v[204:205], v[148:149], v[92:93], v[204:205] op_sel:[0,0,0] op_sel_hi:[1,0,1]
	v_pk_fma_f32 v[206:207], v[148:149], v[94:95], v[206:207] op_sel:[0,0,0] op_sel_hi:[1,0,1]
	s_waitcnt lgkmcnt(1)
; __device__ __forceinline__ unsigned f2bf(float f) { unsigned u = __float_as_uint(f); return (u + 0x7fffu + ((u >> 16) & 1u)) >> 16; }
;     static __device__ __forceinline__ void run(float (&acc)[32], const float (&w)[31], const LAS float* us) {
;     ...
;         for (int t = TLO; t <= THI; ++t) acc[t] += v * w[J - t];
; __device__ __forceinline__ void cf_prompt_items(LAS unsigned char* lds, const bf16_t* PROJ, int it0, int itstride, int nitems, const float* cw, const float* cb, bf16_t* CONVOUT, float* pcfc) {
;     ...
;         for (int t = 0; t < 32; ++t) CONVOUT[(size_t)(row0 + t) * DM + c0 + tid] = (bf16_t)f2bf(acc[t]);
	v_pk_fma_f32 v[206:207], v[150:151], v[92:93], v[206:207] op_sel:[0,1,0] op_sel_hi:[1,1,1]
	s_waitcnt lgkmcnt(0)
	v_pk_fma_f32 v[206:207], v[152:153], v[92:93], v[206:207] op_sel:[0,0,0] op_sel_hi:[1,0,1]
	v_mov_b32_e32 v36, v176
	v_mov_b32_e32 v13, v177
	v_mov_b32_e32 v38, v178
	v_mov_b32_e32 v37, v179
	v_mov_b32_e32 v40, v180
	v_mov_b32_e32 v39, v181
	v_mov_b32_e32 v41, v182
	v_mov_b32_e32 v42, v183
	v_mov_b32_e32 v43, v184
	v_mov_b32_e32 v47, v185
	v_mov_b32_e32 v107, v186
	v_mov_b32_e32 v109, v187
	v_mov_b32_e32 v110, v188
	v_mov_b32_e32 v112, v189
	v_mov_b32_e32 v113, v190
	v_mov_b32_e32 v115, v191
	v_mov_b32_e32 v116, v192
	v_mov_b32_e32 v118, v193
	v_mov_b32_e32 v119, v194
	v_mov_b32_e32 v121, v195
	v_mov_b32_e32 v122, v196
	v_mov_b32_e32 v124, v197
	v_mov_b32_e32 v125, v198
	v_mov_b32_e32 v128, v199
	v_mov_b32_e32 v129, v200
	v_mov_b32_e32 v130, v201
	v_mov_b32_e32 v131, v202
	v_mov_b32_e32 v132, v203
	v_mov_b32_e32 v133, v204
	v_mov_b32_e32 v134, v205
	v_mov_b32_e32 v135, v206
	v_mov_b32_e32 v91, v207
	v_lshl_add_u64 v[14:15], v[48:49], 0, s[38:39]
	v_bfe_u32 v92, v36, 16, 1
	v_add3_u32 v36, v36, v92, s90
	v_lshl_add_u64 v[92:93], v[14:15], 0, s[0:1]
	s_or_b32 s0, s82, 1
	s_ashr_i32 s1, s0, 31
	s_lshl_b64 s[0:1], s[0:1], 12
	global_store_short_d16_hi v[92:93], v36, off
	v_lshl_add_u64 v[92:93], v[14:15], 0, s[0:1]
	s_or_b32 s0, s82, 2
	v_bfe_u32 v36, v13, 16, 1
	s_ashr_i32 s1, s0, 31
	v_add3_u32 v13, v13, v36, s90
	s_lshl_b64 s[0:1], s[0:1], 12
	global_store_short_d16_hi v[92:93], v13, off
	v_bfe_u32 v13, v38, 16, 1
	v_lshl_add_u64 v[92:93], v[14:15], 0, s[0:1]
	s_or_b32 s0, s82, 3
	v_add3_u32 v13, v38, v13, s90
	s_ashr_i32 s1, s0, 31
	global_store_short_d16_hi v[92:93], v13, off
	v_bfe_u32 v13, v37, 16, 1
	s_lshl_b64 s[0:1], s[0:1], 12
	v_add3_u32 v13, v37, v13, s90
	v_lshl_add_u64 v[36:37], v[14:15], 0, s[0:1]
	s_or_b32 s0, s82, 4
	s_ashr_i32 s1, s0, 31
	s_lshl_b64 s[0:1], s[0:1], 12
	global_store_short_d16_hi v[36:37], v13, off
	v_lshl_add_u64 v[36:37], v[14:15], 0, s[0:1]
	s_or_b32 s0, s82, 5
	v_bfe_u32 v13, v40, 16, 1
	s_ashr_i32 s1, s0, 31
	v_add3_u32 v13, v40, v13, s90
	s_lshl_b64 s[0:1], s[0:1], 12
	global_store_short_d16_hi v[36:37], v13, off
	v_lshl_add_u64 v[36:37], v[14:15], 0, s[0:1]
	s_or_b32 s0, s82, 6
	v_bfe_u32 v13, v39, 16, 1
	s_ashr_i32 s1, s0, 31
	v_add3_u32 v13, v39, v13, s90
	s_lshl_b64 s[0:1], s[0:1], 12
	global_store_short_d16_hi v[36:37], v13, off
	v_lshl_add_u64 v[36:37], v[14:15], 0, s[0:1]
	s_or_b32 s0, s82, 7
	v_bfe_u32 v13, v41, 16, 1
	s_ashr_i32 s1, s0, 31
	v_add3_u32 v13, v41, v13, s90
	s_lshl_b64 s[0:1], s[0:1], 12
	global_store_short_d16_hi v[36:37], v13, off
	v_lshl_add_u64 v[36:37], v[14:15], 0, s[0:1]
	s_or_b32 s0, s82, 8
	v_bfe_u32 v13, v42, 16, 1
	s_ashr_i32 s1, s0, 31
	v_add3_u32 v13, v42, v13, s90
	s_lshl_b64 s[0:1], s[0:1], 12
	global_store_short_d16_hi v[36:37], v13, off
	v_lshl_add_u64 v[36:37], v[14:15], 0, s[0:1]
	s_or_b32 s0, s82, 9
	v_bfe_u32 v13, v43, 16, 1
	s_ashr_i32 s1, s0, 31
	v_add3_u32 v13, v43, v13, s90
	s_lshl_b64 s[0:1], s[0:1], 12
	global_store_short_d16_hi v[36:37], v13, off
	v_lshl_add_u64 v[36:37], v[14:15], 0, s[0:1]
	s_or_b32 s0, s82, 10
	v_bfe_u32 v13, v47, 16, 1
	s_ashr_i32 s1, s0, 31
	v_add3_u32 v13, v47, v13, s90
	s_lshl_b64 s[0:1], s[0:1], 12
	global_store_short_d16_hi v[36:37], v13, off
	v_lshl_add_u64 v[36:37], v[14:15], 0, s[0:1]
	s_or_b32 s0, s82, 11
	v_bfe_u32 v13, v107, 16, 1
	s_ashr_i32 s1, s0, 31
	v_add3_u32 v13, v107, v13, s90
	s_lshl_b64 s[0:1], s[0:1], 12
	global_store_short_d16_hi v[36:37], v13, off
	v_lshl_add_u64 v[36:37], v[14:15], 0, s[0:1]
	s_or_b32 s0, s82, 12
	v_bfe_u32 v13, v109, 16, 1
	s_ashr_i32 s1, s0, 31
	v_add3_u32 v13, v109, v13, s90
	s_lshl_b64 s[0:1], s[0:1], 12
	global_store_short_d16_hi v[36:37], v13, off
	v_lshl_add_u64 v[36:37], v[14:15], 0, s[0:1]
	s_or_b32 s0, s82, 13
	v_bfe_u32 v13, v110, 16, 1
	s_ashr_i32 s1, s0, 31
	v_add3_u32 v13, v110, v13, s90
	s_lshl_b64 s[0:1], s[0:1], 12
	global_store_short_d16_hi v[36:37], v13, off
	v_lshl_add_u64 v[36:37], v[14:15], 0, s[0:1]
	s_or_b32 s0, s82, 14
	v_bfe_u32 v13, v112, 16, 1
	s_ashr_i32 s1, s0, 31
	v_add3_u32 v13, v112, v13, s90
; __device__ __forceinline__ unsigned f2bf(float f) { unsigned u = __float_as_uint(f); return (u + 0x7fffu + ((u >> 16) & 1u)) >> 16; }
; #define LDS_BARRIER() do { asm volatile("s_waitcnt lgkmcnt(0)" ::: "memory"); __builtin_amdgcn_s_barrier(); asm volatile("" ::: "memory"); } while (0)
; __device__ __forceinline__ void cf_prompt_items(LAS unsigned char* lds, const bf16_t* PROJ, int it0, int itstride, int nitems, const float* cw, const float* cb, bf16_t* CONVOUT, float* pcfc) {
;     ...
;         for (int t = 0; t < 32; ++t) CONVOUT[(size_t)(row0 + t) * DM + c0 + tid] = (bf16_t)f2bf(acc[t]);
;         LDS_BARRIER();
	s_lshl_b64 s[0:1], s[0:1], 12
	global_store_short_d16_hi v[36:37], v13, off
	v_lshl_add_u64 v[36:37], v[14:15], 0, s[0:1]
	s_or_b32 s0, s82, 15
	v_bfe_u32 v13, v113, 16, 1
	s_ashr_i32 s1, s0, 31
	v_add3_u32 v13, v113, v13, s90
	s_lshl_b64 s[0:1], s[0:1], 12
	global_store_short_d16_hi v[36:37], v13, off
	v_lshl_add_u64 v[36:37], v[14:15], 0, s[0:1]
	s_or_b32 s0, s82, 16
	v_bfe_u32 v13, v115, 16, 1
	s_ashr_i32 s1, s0, 31
	v_add3_u32 v13, v115, v13, s90
	s_lshl_b64 s[0:1], s[0:1], 12
	global_store_short_d16_hi v[36:37], v13, off
	v_lshl_add_u64 v[36:37], v[14:15], 0, s[0:1]
	s_or_b32 s0, s82, 17
	v_bfe_u32 v13, v116, 16, 1
	s_ashr_i32 s1, s0, 31
	v_add3_u32 v13, v116, v13, s90
	s_lshl_b64 s[0:1], s[0:1], 12
	global_store_short_d16_hi v[36:37], v13, off
	v_lshl_add_u64 v[36:37], v[14:15], 0, s[0:1]
	s_or_b32 s0, s82, 18
	v_bfe_u32 v13, v118, 16, 1
	s_ashr_i32 s1, s0, 31
	v_add3_u32 v13, v118, v13, s90
	s_lshl_b64 s[0:1], s[0:1], 12
	global_store_short_d16_hi v[36:37], v13, off
	v_lshl_add_u64 v[36:37], v[14:15], 0, s[0:1]
	s_or_b32 s0, s82, 19
	v_bfe_u32 v13, v119, 16, 1
	s_ashr_i32 s1, s0, 31
	v_add3_u32 v13, v119, v13, s90
	s_lshl_b64 s[0:1], s[0:1], 12
	global_store_short_d16_hi v[36:37], v13, off
	v_lshl_add_u64 v[36:37], v[14:15], 0, s[0:1]
	s_or_b32 s0, s82, 20
	v_bfe_u32 v13, v121, 16, 1
	s_ashr_i32 s1, s0, 31
	v_add3_u32 v13, v121, v13, s90
	s_lshl_b64 s[0:1], s[0:1], 12
	global_store_short_d16_hi v[36:37], v13, off
	v_lshl_add_u64 v[36:37], v[14:15], 0, s[0:1]
	s_or_b32 s0, s82, 21
	v_bfe_u32 v13, v122, 16, 1
	s_ashr_i32 s1, s0, 31
	v_add3_u32 v13, v122, v13, s90
	s_lshl_b64 s[0:1], s[0:1], 12
	global_store_short_d16_hi v[36:37], v13, off
	v_lshl_add_u64 v[36:37], v[14:15], 0, s[0:1]
	s_or_b32 s0, s82, 22
	v_bfe_u32 v13, v124, 16, 1
	s_ashr_i32 s1, s0, 31
	v_add3_u32 v13, v124, v13, s90
	s_lshl_b64 s[0:1], s[0:1], 12
	global_store_short_d16_hi v[36:37], v13, off
	v_lshl_add_u64 v[36:37], v[14:15], 0, s[0:1]
	s_or_b32 s0, s82, 23
	v_bfe_u32 v13, v125, 16, 1
	s_ashr_i32 s1, s0, 31
	v_add3_u32 v13, v125, v13, s90
	s_lshl_b64 s[0:1], s[0:1], 12
	global_store_short_d16_hi v[36:37], v13, off
	v_lshl_add_u64 v[36:37], v[14:15], 0, s[0:1]
	s_or_b32 s0, s75, 24
	v_bfe_u32 v13, v128, 16, 1
	s_ashr_i32 s1, s0, 31
	v_add3_u32 v13, v128, v13, s90
	s_lshl_b64 s[0:1], s[0:1], 12
	global_store_short_d16_hi v[36:37], v13, off
	v_lshl_add_u64 v[36:37], v[14:15], 0, s[0:1]
	s_or_b32 s0, s75, 25
	v_bfe_u32 v13, v129, 16, 1
	s_ashr_i32 s1, s0, 31
	v_add3_u32 v13, v129, v13, s90
	s_lshl_b64 s[0:1], s[0:1], 12
	global_store_short_d16_hi v[36:37], v13, off
	v_lshl_add_u64 v[36:37], v[14:15], 0, s[0:1]
	s_or_b32 s0, s75, 26
	v_bfe_u32 v13, v130, 16, 1
	s_ashr_i32 s1, s0, 31
	v_add3_u32 v13, v130, v13, s90
	s_lshl_b64 s[0:1], s[0:1], 12
	global_store_short_d16_hi v[36:37], v13, off
	v_lshl_add_u64 v[36:37], v[14:15], 0, s[0:1]
	s_or_b32 s0, s75, 27
	v_bfe_u32 v13, v131, 16, 1
	s_ashr_i32 s1, s0, 31
	v_add3_u32 v13, v131, v13, s90
	s_lshl_b64 s[0:1], s[0:1], 12
	global_store_short_d16_hi v[36:37], v13, off
	v_lshl_add_u64 v[36:37], v[14:15], 0, s[0:1]
	s_or_b32 s0, s75, 28
	v_bfe_u32 v13, v132, 16, 1
	s_ashr_i32 s1, s0, 31
	v_add3_u32 v13, v132, v13, s90
	s_lshl_b64 s[0:1], s[0:1], 12
	global_store_short_d16_hi v[36:37], v13, off
	v_lshl_add_u64 v[36:37], v[14:15], 0, s[0:1]
	s_or_b32 s0, s75, 29
	v_bfe_u32 v13, v133, 16, 1
	s_ashr_i32 s1, s0, 31
	v_add3_u32 v13, v133, v13, s90
	s_lshl_b64 s[0:1], s[0:1], 12
	global_store_short_d16_hi v[36:37], v13, off
	v_lshl_add_u64 v[36:37], v[14:15], 0, s[0:1]
	s_or_b32 s0, s75, 30
	v_bfe_u32 v13, v134, 16, 1
	s_ashr_i32 s1, s0, 31
	v_add3_u32 v13, v134, v13, s90
	s_lshl_b64 s[0:1], s[0:1], 12
	global_store_short_d16_hi v[36:37], v13, off
	v_bfe_u32 v13, v135, 16, 1
	v_lshl_add_u64 v[36:37], v[14:15], 0, s[0:1]
	s_or_b32 s0, s75, 31
	v_add3_u32 v13, v135, v13, s90
	s_ashr_i32 s1, s0, 31
	global_store_short_d16_hi v[36:37], v13, off
	v_bfe_u32 v13, v91, 16, 1
	s_lshl_b64 s[0:1], s[0:1], 12
	v_add3_u32 v13, v91, v13, s90
	v_lshl_add_u64 v[14:15], v[14:15], 0, s[0:1]
	global_store_short_d16_hi v[14:15], v13, off
	s_waitcnt lgkmcnt(0)
	s_barrier
	s_mov_b32 s75, s92
	s_cbranch_vccz .LBB0_293
